# attention: one static s_setprio 1 for waves 4-7 per unit (younger half), reset at unit end
# baseline (speedup 1.0000x reference)
; __device__ __forceinline__ unsigned cvt_pk_bf16(float lo, float hi) { unsigned r; asm volatile("v_cvt_pk_bf16_f32 %0, %1, %2" : "=v"(r) : "v"(lo), "v"(hi)); return r; }
; __device__ __forceinline__ int crow(int r, int hi) { return (r & 3) + 8 * (r >> 2) + 4 * hi; }
; template <bool MLA> ...
;     ...
;   if (hi == 0) li_l[r32] = l_reg; asm volatile("s_waitcnt lgkmcnt(0)" ::: "memory");
;   float rli[16];
; #pragma unroll
;   for (int r = 0; r < 16; ++r) rli[r] = __builtin_amdgcn_rcpf(li_l[crow(r, hi)]);
;   bf16_t* Ow = Ob + (long)(wid * QBLK) * LDO;
; #pragma unroll
;   for (int r = 0; r < 16; ++r) { int orow = crow(r, hi);
; #pragma unroll
;     for (int d0 = 0; d0 < 4; ++d0) Ow[(long)orow * LDO + d0 * 32 + r32] = (bf16_t)(cvt_pk_bf16(o[d0][r] * rli[r], 0.f) & 0xffffu); }
;   __syncthreads();
.LBB0_97:
	s_or_b64 exec, exec, s[2:3]
	s_waitcnt lgkmcnt(0)
	v_add_u32_e32 v0, s10, v166
	ds_read_b128 v[66:69], v0
	ds_read_b128 v[70:73], v0 offset:32
	ds_read_b128 v[74:77], v0 offset:64
	ds_read_b128 v[78:81], v0 offset:96
	s_mul_hi_i32 s3, s11, 0x1800
	s_mulk_i32 s11, 0x1800
	s_add_u32 s2, s4, s11
	s_addc_u32 s3, s5, s3
	v_and_b32_e32 v83, 0x1c0, v184
	v_lshlrev_b32_e32 v83, 7, v83
	v_and_b32_e32 v82, 32, v184
	v_lshl_or_b32 v83, v82, 5, v83
	v_and_b32_e32 v82, 31, v184
	v_lshl_or_b32 v83, v82, 1, v83
	s_waitcnt lgkmcnt(0)
	s_barrier
	v_rcp_f32_e32 v66, v66
	v_rcp_f32_e32 v67, v67
	v_rcp_f32_e32 v68, v68
	v_rcp_f32_e32 v69, v69
	v_rcp_f32_e32 v70, v70
	v_rcp_f32_e32 v71, v71
	v_rcp_f32_e32 v72, v72
	v_rcp_f32_e32 v73, v73
	v_rcp_f32_e32 v74, v74
	v_rcp_f32_e32 v75, v75
	v_rcp_f32_e32 v76, v76
	v_rcp_f32_e32 v77, v77
	v_rcp_f32_e32 v78, v78
	v_rcp_f32_e32 v79, v79
	v_rcp_f32_e32 v80, v80
	v_rcp_f32_e32 v81, v81
	s_nop 0
	v_mul_f32_e32 v82, v2, v66
	v_cvt_pk_bf16_f32 v82, v82, v1
	ds_write_b16 v83, v82 offset:0
	v_mul_f32_e32 v0, v50, v66
	v_cvt_pk_bf16_f32 v0, v0, v1
	ds_write_b16 v83, v0 offset:64
	v_mul_f32_e32 v82, v34, v66
	v_cvt_pk_bf16_f32 v82, v82, v1
	ds_write_b16 v83, v82 offset:128
	v_mul_f32_e32 v0, v18, v66
	v_cvt_pk_bf16_f32 v0, v0, v1
	ds_write_b16 v83, v0 offset:192
	v_mul_f32_e32 v82, v3, v67
	v_cvt_pk_bf16_f32 v82, v82, v1
	ds_write_b16 v83, v82 offset:256
	v_mul_f32_e32 v0, v51, v67
	v_cvt_pk_bf16_f32 v0, v0, v1
	ds_write_b16 v83, v0 offset:320
	v_mul_f32_e32 v82, v35, v67
	v_cvt_pk_bf16_f32 v82, v82, v1
	ds_write_b16 v83, v82 offset:384
	v_mul_f32_e32 v0, v19, v67
	v_cvt_pk_bf16_f32 v0, v0, v1
	ds_write_b16 v83, v0 offset:448
	v_mul_f32_e32 v82, v4, v68
	v_cvt_pk_bf16_f32 v82, v82, v1
	ds_write_b16 v83, v82 offset:512
	v_mul_f32_e32 v0, v52, v68
	v_cvt_pk_bf16_f32 v0, v0, v1
	ds_write_b16 v83, v0 offset:576
	v_mul_f32_e32 v82, v36, v68
	v_cvt_pk_bf16_f32 v82, v82, v1
	ds_write_b16 v83, v82 offset:640
	v_mul_f32_e32 v0, v20, v68
	v_cvt_pk_bf16_f32 v0, v0, v1
	ds_write_b16 v83, v0 offset:704
	v_mul_f32_e32 v82, v5, v69
	v_cvt_pk_bf16_f32 v82, v82, v1
	ds_write_b16 v83, v82 offset:768
	v_mul_f32_e32 v0, v53, v69
	v_cvt_pk_bf16_f32 v0, v0, v1
	ds_write_b16 v83, v0 offset:832
	v_mul_f32_e32 v82, v37, v69
	v_cvt_pk_bf16_f32 v82, v82, v1
	ds_write_b16 v83, v82 offset:896
	v_mul_f32_e32 v0, v21, v69
	v_cvt_pk_bf16_f32 v0, v0, v1
	ds_write_b16 v83, v0 offset:960
	v_mul_f32_e32 v82, v6, v70
	v_cvt_pk_bf16_f32 v82, v82, v1
	ds_write_b16 v83, v82 offset:2048
	v_mul_f32_e32 v0, v54, v70
	v_cvt_pk_bf16_f32 v0, v0, v1
	ds_write_b16 v83, v0 offset:2112
	v_mul_f32_e32 v82, v38, v70
	v_cvt_pk_bf16_f32 v82, v82, v1
	ds_write_b16 v83, v82 offset:2176
	v_mul_f32_e32 v0, v22, v70
	v_cvt_pk_bf16_f32 v0, v0, v1
	ds_write_b16 v83, v0 offset:2240
	v_mul_f32_e32 v82, v7, v71
	v_cvt_pk_bf16_f32 v82, v82, v1
	ds_write_b16 v83, v82 offset:2304
	v_mul_f32_e32 v0, v55, v71
	v_cvt_pk_bf16_f32 v0, v0, v1
	ds_write_b16 v83, v0 offset:2368
	v_mul_f32_e32 v82, v39, v71
	v_cvt_pk_bf16_f32 v82, v82, v1
	ds_write_b16 v83, v82 offset:2432
	v_mul_f32_e32 v0, v23, v71
	v_cvt_pk_bf16_f32 v0, v0, v1
	ds_write_b16 v83, v0 offset:2496
	v_mul_f32_e32 v82, v8, v72
	v_cvt_pk_bf16_f32 v82, v82, v1
	ds_write_b16 v83, v82 offset:2560
	v_mul_f32_e32 v0, v56, v72
	v_cvt_pk_bf16_f32 v0, v0, v1
	ds_write_b16 v83, v0 offset:2624
	v_mul_f32_e32 v82, v40, v72
	v_cvt_pk_bf16_f32 v82, v82, v1
	ds_write_b16 v83, v82 offset:2688
	v_mul_f32_e32 v0, v24, v72
	v_cvt_pk_bf16_f32 v0, v0, v1
	ds_write_b16 v83, v0 offset:2752
	v_mul_f32_e32 v82, v9, v73
	v_cvt_pk_bf16_f32 v82, v82, v1
	ds_write_b16 v83, v82 offset:2816
	v_mul_f32_e32 v0, v57, v73
	v_cvt_pk_bf16_f32 v0, v0, v1
	ds_write_b16 v83, v0 offset:2880
	v_mul_f32_e32 v82, v41, v73
	v_cvt_pk_bf16_f32 v82, v82, v1
	ds_write_b16 v83, v82 offset:2944
	v_mul_f32_e32 v0, v25, v73
	v_cvt_pk_bf16_f32 v0, v0, v1
	ds_write_b16 v83, v0 offset:3008
	v_mul_f32_e32 v82, v10, v74
	v_cvt_pk_bf16_f32 v82, v82, v1
	ds_write_b16 v83, v82 offset:4096
	v_mul_f32_e32 v0, v58, v74
	v_cvt_pk_bf16_f32 v0, v0, v1
	ds_write_b16 v83, v0 offset:4160
	v_mul_f32_e32 v82, v42, v74
	v_cvt_pk_bf16_f32 v82, v82, v1
	ds_write_b16 v83, v82 offset:4224
	v_mul_f32_e32 v0, v26, v74
	v_cvt_pk_bf16_f32 v0, v0, v1
	ds_write_b16 v83, v0 offset:4288
	v_mul_f32_e32 v82, v11, v75
	v_cvt_pk_bf16_f32 v82, v82, v1
	ds_write_b16 v83, v82 offset:4352
	v_mul_f32_e32 v0, v59, v75
	v_cvt_pk_bf16_f32 v0, v0, v1
	ds_write_b16 v83, v0 offset:4416
	v_mul_f32_e32 v82, v43, v75
	v_cvt_pk_bf16_f32 v82, v82, v1
	ds_write_b16 v83, v82 offset:4480
	v_mul_f32_e32 v0, v27, v75
	v_cvt_pk_bf16_f32 v0, v0, v1
	ds_write_b16 v83, v0 offset:4544
	v_mul_f32_e32 v82, v12, v76
	v_cvt_pk_bf16_f32 v82, v82, v1
	ds_write_b16 v83, v82 offset:4608
	v_mul_f32_e32 v0, v60, v76
	v_cvt_pk_bf16_f32 v0, v0, v1
	ds_write_b16 v83, v0 offset:4672
	v_mul_f32_e32 v82, v44, v76
	v_cvt_pk_bf16_f32 v82, v82, v1
	ds_write_b16 v83, v82 offset:4736
	v_mul_f32_e32 v0, v28, v76
	v_cvt_pk_bf16_f32 v0, v0, v1
	ds_write_b16 v83, v0 offset:4800
	v_mul_f32_e32 v82, v13, v77
	v_cvt_pk_bf16_f32 v82, v82, v1
	ds_write_b16 v83, v82 offset:4864
	v_mul_f32_e32 v0, v61, v77
	v_cvt_pk_bf16_f32 v0, v0, v1
	ds_write_b16 v83, v0 offset:4928
	v_mul_f32_e32 v82, v45, v77
	v_cvt_pk_bf16_f32 v82, v82, v1
	ds_write_b16 v83, v82 offset:4992
	v_mul_f32_e32 v0, v29, v77
	v_cvt_pk_bf16_f32 v0, v0, v1
	ds_write_b16 v83, v0 offset:5056
	v_mul_f32_e32 v82, v14, v78
	v_cvt_pk_bf16_f32 v82, v82, v1
	ds_write_b16 v83, v82 offset:6144
	v_mul_f32_e32 v0, v62, v78
	v_cvt_pk_bf16_f32 v0, v0, v1
	ds_write_b16 v83, v0 offset:6208
	v_mul_f32_e32 v82, v46, v78
	v_cvt_pk_bf16_f32 v82, v82, v1
	ds_write_b16 v83, v82 offset:6272
	v_mul_f32_e32 v0, v30, v78
	v_cvt_pk_bf16_f32 v0, v0, v1
	ds_write_b16 v83, v0 offset:6336
	v_mul_f32_e32 v82, v15, v79
	v_cvt_pk_bf16_f32 v82, v82, v1
	ds_write_b16 v83, v82 offset:6400
	v_mul_f32_e32 v0, v63, v79
	v_cvt_pk_bf16_f32 v0, v0, v1
	ds_write_b16 v83, v0 offset:6464
	v_mul_f32_e32 v82, v47, v79
	v_cvt_pk_bf16_f32 v82, v82, v1
	ds_write_b16 v83, v82 offset:6528
	v_mul_f32_e32 v0, v31, v79
	v_cvt_pk_bf16_f32 v0, v0, v1
	ds_write_b16 v83, v0 offset:6592
	v_mul_f32_e32 v82, v16, v80
	v_cvt_pk_bf16_f32 v82, v82, v1
	ds_write_b16 v83, v82 offset:6656
	v_mul_f32_e32 v0, v64, v80
	v_cvt_pk_bf16_f32 v0, v0, v1
	ds_write_b16 v83, v0 offset:6720
	v_mul_f32_e32 v82, v48, v80
	v_cvt_pk_bf16_f32 v82, v82, v1
	ds_write_b16 v83, v82 offset:6784
	v_mul_f32_e32 v0, v32, v80
	v_cvt_pk_bf16_f32 v0, v0, v1
	ds_write_b16 v83, v0 offset:6848
	v_mul_f32_e32 v82, v17, v81
	v_cvt_pk_bf16_f32 v82, v82, v1
	ds_write_b16 v83, v82 offset:6912
	v_mul_f32_e32 v0, v65, v81
	v_cvt_pk_bf16_f32 v0, v0, v1
	ds_write_b16 v83, v0 offset:6976
	v_mul_f32_e32 v82, v49, v81
	v_cvt_pk_bf16_f32 v82, v82, v1
	ds_write_b16 v83, v82 offset:7040
	v_mul_f32_e32 v0, v33, v81
	v_cvt_pk_bf16_f32 v0, v0, v1
	ds_write_b16 v83, v0 offset:7104
	s_waitcnt lgkmcnt(0)
; __device__ __forceinline__ unsigned cvt_pk_bf16(float lo, float hi) { unsigned r; asm volatile("v_cvt_pk_bf16_f32 %0, %1, %2" : "=v"(r) : "v"(lo), "v"(hi)); return r; }
; __device__ __forceinline__ int crow(int r, int hi) { return (r & 3) + 8 * (r >> 2) + 4 * hi; }
; template <bool MLA> ...
;     ...
;   bf16_t* Ow = Ob + (long)(wid * QBLK) * LDO;
; #pragma unroll
;   for (int r = 0; r < 16; ++r) { int orow = crow(r, hi);
; #pragma unroll
;     for (int d0 = 0; d0 < 4; ++d0) Ow[(long)orow * LDO + d0 * 32 + r32] = (bf16_t)(cvt_pk_bf16(o[d0][r] * rli[r], 0.f) & 0xffffu); }
;   __syncthreads();
	v_and_b32_e32 v2, 0x1c0, v184
	v_lshlrev_b32_e32 v2, 7, v2
	v_and_b32_e32 v3, 63, v184
	v_lshl_or_b32 v2, v3, 4, v2
	ds_read_b128 v[4:7], v2 offset:0
	ds_read_b128 v[8:11], v2 offset:1024
	ds_read_b128 v[12:15], v2 offset:2048
	ds_read_b128 v[16:19], v2 offset:3072
	ds_read_b128 v[20:23], v2 offset:4096
	ds_read_b128 v[24:27], v2 offset:5120
	ds_read_b128 v[28:31], v2 offset:6144
	ds_read_b128 v[32:35], v2 offset:7168
	v_bfe_u32 v36, v184, 4, 2
	v_mul_u32_u24_e32 v36, 0x1800, v36
	v_and_b32_e32 v37, 15, v184
	v_lshl_or_b32 v36, v37, 4, v36
	v_mov_b32_e32 v37, 0
	v_lshl_add_u64 v[38:39], s[2:3], 0, v[36:37]
	s_mov_b64 vcc, 0x6000
	v_lshl_add_u64 v[40:41], v[38:39], 0, vcc
	v_lshl_add_u64 v[42:43], v[40:41], 0, vcc
	v_lshl_add_u64 v[44:45], v[42:43], 0, vcc
	v_lshl_add_u64 v[46:47], v[44:45], 0, vcc
	v_lshl_add_u64 v[48:49], v[46:47], 0, vcc
	v_lshl_add_u64 v[50:51], v[48:49], 0, vcc
	v_lshl_add_u64 v[52:53], v[50:51], 0, vcc
	s_waitcnt lgkmcnt(7)
	global_store_dwordx4 v[38:39], v[4:7], off
	s_waitcnt lgkmcnt(6)
	global_store_dwordx4 v[40:41], v[8:11], off
	s_waitcnt lgkmcnt(5)
	global_store_dwordx4 v[42:43], v[12:15], off
	s_waitcnt lgkmcnt(4)
	global_store_dwordx4 v[44:45], v[16:19], off
	s_waitcnt lgkmcnt(3)
	global_store_dwordx4 v[46:47], v[20:23], off
	s_waitcnt lgkmcnt(2)
	global_store_dwordx4 v[48:49], v[24:27], off
	s_waitcnt lgkmcnt(1)
	global_store_dwordx4 v[50:51], v[28:31], off
	s_waitcnt lgkmcnt(0)
	global_store_dwordx4 v[52:53], v[32:35], off
	s_setprio 0
	s_waitcnt vmcnt(63) expcnt(7) lgkmcnt(15)
	s_barrier

; __device__ __forceinline__ int opaque_tid() { int t = threadIdx.x; asm volatile("" : "+v"(t)); return t; }
; template <bool MLA> ...
;     ...
;   const int tid = opaque_tid(), wid = __builtin_amdgcn_readfirstlane(tid >> 6), lane = tid & 63, r32 = lane & 31, hi = lane >> 5;
;   char* V_lds = lds + OFF_V; char* K_lds = lds + OFF_K; char* KR_lds = lds + OFF_KR;
;   float* ws = (float*)(lds + OFF_WS) + wid * 64; float* li_l = ws; float* al_l = ws + 32;
;   unsigned koff[2], voff[2], kroff = 0;
; #pragma unroll
;   for (int i = 0; i < 2; ++i) { const int p = 2 * wid + i;
;     { const int row = 4 * p + (lane >> 4), pc = lane & 15, c = pc ^ (row & 7); koff[i] = (unsigned)(row * LDK + c * 8) * 2u; }
;     { const int o = p * 1024 + lane * 16, sub = o >> 9, w_ = (o & 511) >> 1, kk = (sub >> 2) * 8 + (w_ >> 5), k = (kk & ~0xC) | ((kk & 4) << 1) | ((kk & 8) >> 1), c = (sub & 3) * 32 + (w_ & 31);
;       voff[i] = (unsigned)(k * LDK + c) * 2u; } }
;   if constexpr (MLA) { const int row = 8 * wid + (lane >> 3), pc = lane & 7, ch = pc ^ ((row >> 1) & 7); kroff = (unsigned)(row * LDKR + ch * 8) * 2u; }
;     ...
;   DMA_TILE(0, 0); DMA_TILE(1, 1);
;   float l_reg = 0, m_reg = 0; f32x16 o[4] = {}; bf16x8 qr[8]; f32x16 negm = {}; asm volatile("" : "+v"(negm));
;   char* qrl = lds + OFF_QR + wid * 4096 + lane * 16;
;   { const bf16_t* Qw = Qb + (long)(wid * QBLK + r32) * LDQ + hi * 8;
; #pragma unroll
;     for (int d0 = 0; d0 < 8; ++d0) qr[d0] = *reinterpret_cast<const bf16x8*>(Qw + d0 * 16);
;     if constexpr (MLA) { const bf16_t* Qw2 = Qrb + (long)(wid * QBLK + r32) * LDQ + hi * 8;
; #pragma unroll
;       for (int d0 = 0; d0 < 4; ++d0) *reinterpret_cast<bf16x8*>(qrl + d0 * 1024) = *reinterpret_cast<const bf16x8*>(Qw2 + d0 * 16); } }
; __global__ void __launch_bounds__(512) mega_fwd(Params p) {
;     ...
;             for (int u = bx; u < 3072; u += G) {
;                 const int mla = u / 1536, v = u % 1536, grp = v >> 8, w = v & 255, bh = grp * 8 + (w & 7), qb = w >> 3, b = bh >> 3, h = bh & 7;
;                 const size_t row0 = (size_t)b * SEQ, q0 = row0 + (size_t)qb * 256;
.LBB0_99:
	s_mul_hi_i32 s2, s12, 0x2aaaaaab
	s_lshr_b32 s3, s2, 31
	s_lshr_b32 s2, s2, 8
	s_add_i32 s2, s2, s3
	s_mulk_i32 s2, 0x600
	s_sub_i32 s13, s12, s2
	s_ashr_i32 s8, s13, 8
	s_ashr_i32 s9, s8, 31
	s_lshl_b32 s4, s13, 5
	s_lshl_b64 s[2:3], s[8:9], 13
	s_and_b32 s4, s4, 0x1f00
	s_or_b32 s2, s2, s4
	s_mulk_i32 s3, 0x1800
	s_mul_hi_u32 s5, s2, 0x1800
	s_and_b32 s16, s13, 7
	s_add_i32 s4, s12, 0x5ff
	s_add_i32 s5, s5, s3
	s_mulk_i32 s2, 0x1800
	s_add_u32 s17, s92, s2
	s_addc_u32 s18, s93, s5
	s_cmpk_gt_u32 s4, 0xbfe
	s_mov_b64 s[2:3], -1
	s_cbranch_scc0 .LBB0_115
	s_lshl_b32 s2, s16, 7
	s_lshl_b32 s3, s16, 8
	s_add_u32 s4, s17, s3
	s_addc_u32 s5, s18, 0
	s_add_u32 s2, s17, s2
	s_addc_u32 s3, s18, 0
	s_add_u32 s6, s2, 0x1000
	s_addc_u32 s7, s3, 0
	s_lshl_b64 s[2:3], s[8:9], 25
	s_add_u32 s10, s82, s2
	s_addc_u32 s11, s83, s3
	s_lshl_b32 s30, s16, 9
	s_add_u32 s24, s10, s30
	s_addc_u32 s25, s11, 0
	s_lshl_b64 s[10:11], s[8:9], 24
	v_readlane_b32 s14, v248, 43
	s_waitcnt vmcnt(0)
	v_mov_b32_e32 v64, v184
	v_readlane_b32 s15, v248, 44
	s_add_u32 s36, s14, s10
	s_addc_u32 s37, s15, s11
	v_readfirstlane_b32 s9, v64
	s_ashr_i32 s27, s9, 6
	s_cmp_lt_u32 s27, 4
	s_cbranch_scc1 .Lprio_skip_mla
	s_setprio 1
.Lprio_skip_mla:
	v_and_b32_e32 v98, 63, v64
	s_lshl_b32 s14, s27, 3
	v_lshlrev_b32_e32 v82, 3, v98
	v_lshrrev_b32_e32 v66, 1, v64
	v_bfe_u32 v65, v64, 4, 2
	v_and_b32_e32 v2, 15, v64
	v_bfe_u32 v99, v64, 2, 2
	s_and_b32 s31, s14, 0xffff0
	v_and_b32_e32 v100, 8, v66
	s_lshl_b32 s15, s27, 2
	v_and_b32_e32 v83, 24, v82
	v_bfe_u32 v103, v64, 3, 3
	s_and_b32 s34, s15, 4
	v_or3_b32 v0, v100, v99, s31
	v_and_or_b32 v3, v64, 32, v83
	v_bitop3_b32 v2, v65, v2, 4 bitop3:0x36
	v_or_b32_e32 v9, s14, v103
	v_or_b32_e32 v0, s34, v0
	v_lshlrev_b32_e32 v3, 1, v3
	v_lshlrev_b32_e32 v102, 4, v2
	s_and_b32 s32, s27, 1
	s_lshl_b32 s32, s32, 7
	v_xor_b32_e32 v102, s32, v102
	v_lshrrev_b32_e32 v2, 1, v9
	v_bitop3_b32 v5, v65, v64, 15 bitop3:0x78
	v_lshl_or_b32 v0, v0, 12, v3
	v_or_b32_e32 v3, 4, v65
	v_xor_b32_e32 v2, v2, v64
	s_lshl_b32 s15, s27, 11
	v_or_b32_e32 v4, s14, v65
	v_lshlrev_b32_e32 v101, 4, v5
	v_xor_b32_e32 v101, s32, v101
	v_or_b32_e32 v3, s14, v3
	v_lshlrev_b32_e32 v2, 4, v2
	s_add_i32 s19, s15, 0
	v_lshl_or_b32 v6, v4, 12, v101
	v_lshl_or_b32 v7, v3, 12, v102
	v_and_b32_e32 v104, 0x70, v2
	s_add_i32 m0, s19, 0xc000
	v_lshl_add_u64 v[2:3], s[24:25], 0, v[0:1]
	s_mov_b64 s[38:39], 0x100
	global_load_lds_dwordx4 v6, s[24:25]
	v_lshl_add_u64 v[4:5], v[2:3], 0, s[38:39]
	s_mov_b32 m0, s19
	s_and_b32 s9, s9, 0x3fffffc0
	global_load_lds_dwordx4 v[4:5], off
	s_add_i32 m0, s19, 0xc400
	s_mov_b64 s[38:39], 0x180
	s_lshl_b32 s9, s9, 2
	global_load_lds_dwordx4 v7, s[24:25]
	v_lshl_add_u64 v[2:3], v[2:3], 0, s[38:39]
	s_add_i32 m0, s19, 0x400
	s_add_i32 s9, s9, 0
	global_load_lds_dwordx4 v[2:3], off
	v_lshl_or_b32 v2, v9, 11, v104
	v_mov_b32_e32 v3, v1
	s_lshl_b32 s14, s27, 10
	s_add_i32 s26, 0, 0x18000
	s_add_i32 s9, s9, 0x1e000
	v_lshl_add_u64 v[2:3], s[36:37], 0, v[2:3]
	s_mov_b64 s[36:37], 0x600
	s_add_i32 s23, s26, s14
	v_lshl_add_u64 v[4:5], v[2:3], 0, s[36:37]
	s_add_u32 s36, s24, 0x40000
	s_addc_u32 s37, s25, 0
	s_mov_b32 m0, s23
	s_add_u32 s24, s24, 0x40100
	global_load_lds_dwordx4 v[4:5], off
	s_addc_u32 s25, s25, 0
	s_add_i32 m0, s19, 0x10000
	v_or_b32_e32 v8, 0x80, v0
	global_load_lds_dwordx4 v6, s[36:37]
	s_add_i32 m0, s19, 0x4000
	s_add_i32 s14, s14, 0
	global_load_lds_dwordx4 v0, s[24:25]
	s_add_i32 m0, s19, 0x10400
	v_and_b32_e32 v193, 31, v64
	global_load_lds_dwordx4 v7, s[36:37]
	s_add_i32 m0, s19, 0x4400
	v_bfe_u32 v194, v64, 5, 1
	global_load_lds_dwordx4 v8, s[24:25]
	s_mov_b64 s[24:25], 0x20600
	v_lshl_add_u64 v[2:3], v[2:3], 0, s[24:25]
	s_add_i32 m0, s14, 0x1a000
	s_lshl_b32 s14, s27, 5
	global_load_lds_dwordx4 v[2:3], off
	v_or_b32_e32 v0, s14, v193
	v_mov_b64_e32 v[2:3], s[6:7]
	v_lshlrev_b32_e32 v166, 4, v194
	v_mov_b32_e32 v167, v1
	v_mad_i64_i32 v[2:3], s[6:7], v0, s33, v[2:3]
	v_mov_b32_e32 v16, v1
	v_mov_b32_e32 v17, v1
	v_mov_b32_e32 v18, v1
	v_mov_b32_e32 v19, v1
	v_mov_b32_e32 v20, v1
	v_mov_b32_e32 v21, v1
	v_mov_b32_e32 v22, v1
	v_mov_b32_e32 v23, v1
	v_mov_b32_e32 v24, v1
	v_mov_b32_e32 v25, v1
	v_mov_b32_e32 v26, v1
	v_mov_b32_e32 v27, v1
	v_mov_b32_e32 v28, v1
	v_mov_b32_e32 v29, v1
	v_mov_b32_e32 v30, v1
	v_mov_b32_e32 v31, v1
	v_lshl_add_u64 v[14:15], v[2:3], 0, v[166:167]
	global_load_dwordx4 v[2:5], v[14:15], off
	global_load_dwordx4 v[6:9], v[14:15], off offset:32
	global_load_dwordx4 v[10:13], v[14:15], off offset:64
	global_load_dwordx4 v[32:35], v[14:15], off offset:96
	v_mov_b64_e32 v[14:15], s[4:5]
	v_mad_i64_i32 v[14:15], s[6:7], v0, s33, v[14:15]
	v_lshl_add_u64 v[14:15], v[14:15], 0, v[166:167]
	global_load_dwordx4 v[158:161], v[14:15], off offset:2048
	global_load_dwordx4 v[154:157], v[14:15], off offset:2080
	global_load_dwordx4 v[150:153], v[14:15], off offset:2112
	global_load_dwordx4 v[146:149], v[14:15], off offset:2144
	global_load_dwordx4 v[142:145], v[14:15], off offset:2176
	global_load_dwordx4 v[138:141], v[14:15], off offset:2208
	global_load_dwordx4 v[134:137], v[14:15], off offset:2240
	global_load_dwordx4 v[130:133], v[14:15], off offset:2272
	s_lshl_b32 s6, s27, 12
	s_add_i32 s6, s6, 0
	v_lshlrev_b32_e32 v84, 4, v98
	s_add_i32 s6, s6, 0x1e800
	v_add_u32_e32 v198, s6, v84
	s_waitcnt vmcnt(0)
	ds_write_b128 v198, v[2:5]
	ds_write_b128 v198, v[6:9] offset:1024
	ds_write_b128 v198, v[10:13] offset:2048
	ds_write_b128 v198, v[32:35] offset:3072
	v_lshlrev_b32_e32 v2, 4, v64
	v_lshlrev_b32_e32 v0, 8, v193
	v_and_b32_e32 v10, 0xf0, v2
	v_bitop3_b32 v210, v166, v0, v10 bitop3:0xde
	v_add_u32_e32 v6, 0, v210
	s_waitcnt vmcnt(0)
	s_waitcnt lgkmcnt(0)
	s_barrier
; #define WAIT_BAR() do { asm volatile("s_waitcnt vmcnt(0)" ::: "memory"); __syncthreads(); } while (0)
; template <bool MLA>
; __device__ __forceinline__ void qkt(f32x16& p0, f32x16& p1, const char* Ks, const char* KRs, const bf16x8* qr, const char* qrl, const f32x16& negm, int r32, int hi) {
; #pragma unroll
;   for (int d0 = 0; d0 < 8; ++d0) { int cb = (d0 * 16 + hi * 8) * 2;
;     bf16x8 b0 = *reinterpret_cast<const bf16x8*>(Ks + KSWZ(r32, cb));
;     bf16x8 b1 = *reinterpret_cast<const bf16x8*>(Ks + KSWZ(32 + r32, cb));
;     if (d0 == 0) { p0 = __builtin_amdgcn_mfma_f32_32x32x16_bf16(b0, qr[0], negm, 0, 0, 0); p1 = __builtin_amdgcn_mfma_f32_32x32x16_bf16(b1, qr[0], negm, 0, 0, 0); }
;     else { p0 = __builtin_amdgcn_mfma_f32_32x32x16_bf16(b0, qr[d0], p0, 0, 0, 0); p1 = __builtin_amdgcn_mfma_f32_32x32x16_bf16(b1, qr[d0], p1, 0, 0, 0); } }
;   if constexpr (MLA) {
; #pragma unroll
;     for (int d0 = 0; d0 < 4; ++d0) { int ch = d0 * 2 + hi;
;       bf16x8 b0 = *reinterpret_cast<const bf16x8*>(KRs + KRSWZ(r32, ch));
;       bf16x8 b1 = *reinterpret_cast<const bf16x8*>(KRs + KRSWZ(32 + r32, ch));
;       const bf16x8 qq = *reinterpret_cast<const bf16x8*>(qrl + d0 * 1024);
;       p0 = __builtin_amdgcn_mfma_f32_32x32x16_bf16(b0, qq, p0, 0, 0, 0);
;       p1 = __builtin_amdgcn_mfma_f32_32x32x16_bf16(b1, qq, p1, 0, 0, 0); }
;   }
; template <bool MLA> ...
;     ...
;   WAIT_BAR();
;   qkt<MLA>(pA0, pA1, K_lds, KR_lds, qr, qrl, negm, r32, hi); partialSM<true, false>(pA0, pA1, negm, m_reg, alA);
	ds_read_b128 v[2:5], v6 offset:49152
	ds_read_b128 v[6:9], v6 offset:57344
	s_waitcnt lgkmcnt(1)
	v_mfma_f32_32x32x16_bf16 v[48:63], v[2:5], v[158:161], v[16:31]
	v_or_b32_e32 v2, 32, v166
	v_bitop3_b32 v209, v2, v0, v10 bitop3:0xde
	v_lshlrev_b32_e32 v14, 7, v193
	v_bfe_u32 v15, v64, 1, 3
	v_lshlrev_b32_e32 v105, 1, v64
	s_movk_i32 s6, 0xc0
	s_cmp_lg_u32 0, -1
	s_waitcnt lgkmcnt(0)
	v_mfma_f32_32x32x16_bf16 v[32:47], v[6:9], v[158:161], v[16:31]
	v_add_u32_e32 v6, 0, v209
	ds_read_b128 v[2:5], v6 offset:49152
	ds_read_b128 v[6:9], v6 offset:57344
	s_mov_b32 s25, 2
	s_mov_b32 s24, 1
	s_mov_b32 s35, 0
	v_lshl_add_u32 v167, v193, 2, s9
	v_mov_b32_e32 v195, 0
	s_waitcnt lgkmcnt(1)
	v_mfma_f32_32x32x16_bf16 v[48:63], v[2:5], v[154:157], v[48:63]
	v_or_b32_e32 v2, 64, v166
	v_bitop3_b32 v208, v2, v0, v10 bitop3:0xde
	v_mov_b32_e32 v211, 1.0
	s_waitcnt lgkmcnt(0)
	v_mfma_f32_32x32x16_bf16 v[32:47], v[6:9], v[154:157], v[32:47]
	v_add_u32_e32 v6, 0, v208
	ds_read_b128 v[2:5], v6 offset:49152
	ds_read_b128 v[6:9], v6 offset:57344
	s_waitcnt lgkmcnt(1)
	v_mfma_f32_32x32x16_bf16 v[48:63], v[2:5], v[150:153], v[48:63]
	v_or_b32_e32 v2, 0x60, v166
	v_bitop3_b32 v207, v2, v0, v10 bitop3:0xde
	s_waitcnt lgkmcnt(0)
	v_mfma_f32_32x32x16_bf16 v[32:47], v[6:9], v[150:153], v[32:47]
	v_add_u32_e32 v6, 0, v207
	ds_read_b128 v[2:5], v6 offset:49152
	ds_read_b128 v[6:9], v6 offset:57344
	s_waitcnt lgkmcnt(1)
	v_mfma_f32_32x32x16_bf16 v[48:63], v[2:5], v[146:149], v[48:63]
	v_or_b32_e32 v2, 0x80, v166
	v_bitop3_b32 v206, v2, v0, v10 bitop3:0xde
	s_waitcnt lgkmcnt(0)
	v_mfma_f32_32x32x16_bf16 v[32:47], v[6:9], v[146:149], v[32:47]
	v_add_u32_e32 v6, 0, v206
	ds_read_b128 v[2:5], v6 offset:49152
	ds_read_b128 v[6:9], v6 offset:57344
	s_waitcnt lgkmcnt(1)
	v_mfma_f32_32x32x16_bf16 v[48:63], v[2:5], v[142:145], v[48:63]
	v_or_b32_e32 v2, 0xa0, v166
	v_bitop3_b32 v205, v2, v0, v10 bitop3:0xde
	s_waitcnt lgkmcnt(0)
	v_mfma_f32_32x32x16_bf16 v[32:47], v[6:9], v[142:145], v[32:47]
	v_add_u32_e32 v6, 0, v205
	ds_read_b128 v[2:5], v6 offset:49152
	ds_read_b128 v[6:9], v6 offset:57344
	s_waitcnt lgkmcnt(1)
	v_mfma_f32_32x32x16_bf16 v[48:63], v[2:5], v[138:141], v[48:63]
	v_or_b32_e32 v2, 0xc0, v166
	v_bitop3_b32 v204, v2, v0, v10 bitop3:0xde
	s_waitcnt lgkmcnt(0)
	v_mfma_f32_32x32x16_bf16 v[32:47], v[6:9], v[138:141], v[32:47]
	v_add_u32_e32 v6, 0, v204
	ds_read_b128 v[2:5], v6 offset:49152
	ds_read_b128 v[6:9], v6 offset:57344
	s_waitcnt lgkmcnt(1)
	v_mfma_f32_32x32x16_bf16 v[48:63], v[2:5], v[134:137], v[48:63]
	v_or_b32_e32 v2, 0xe0, v166
	v_bitop3_b32 v203, v2, v0, v10 bitop3:0xde
	v_add_u32_e32 v0, 0, v203
	s_waitcnt lgkmcnt(0)
	v_mfma_f32_32x32x16_bf16 v[32:47], v[6:9], v[134:137], v[32:47]
	ds_read_b128 v[2:5], v0 offset:49152
	ds_read_b128 v[6:9], v0 offset:57344
	v_bitop3_b32 v0, v194, v66, 7 bitop3:0x78
	v_lshl_or_b32 v200, v0, 4, v14
	v_add_u32_e32 v0, s26, v200
	s_waitcnt lgkmcnt(1)
	v_mfma_f32_32x32x16_bf16 v[48:63], v[2:5], v[130:133], v[48:63]
	s_waitcnt lgkmcnt(0)
	v_mfma_f32_32x32x16_bf16 v[32:47], v[6:9], v[130:133], v[32:47]
	ds_read_b128 v[2:5], v0
	ds_read_b128 v[6:9], v198
	ds_read_b128 v[10:13], v0 offset:4096
	ds_read_b128 v[66:69], v198 offset:1024
	v_bitop3_b32 v0, v194, v15, 2 bitop3:0x36
	v_lshl_or_b32 v201, v0, 4, v14
	v_mov_b32_e32 v0, v1
	s_waitcnt lgkmcnt(2)
	v_mfma_f32_32x32x16_bf16 v[48:63], v[2:5], v[6:9], v[48:63]
	s_waitcnt lgkmcnt(1)
	v_mfma_f32_32x32x16_bf16 v[32:47], v[10:13], v[6:9], v[32:47]
	v_add_u32_e32 v6, s26, v201
	ds_read_b128 v[2:5], v6
	ds_read_b128 v[6:9], v6 offset:4096
	s_waitcnt lgkmcnt(1)
	v_mfma_f32_32x32x16_bf16 v[48:63], v[2:5], v[66:69], v[48:63]
	v_bitop3_b32 v5, v194, v15, 4 bitop3:0x36
	v_lshl_or_b32 v199, v5, 4, v14
	v_add_u32_e32 v70, s26, v199
	ds_read_b128 v[10:13], v70
	v_mov_b32_e32 v2, v1
	v_mov_b32_e32 v3, v1
	v_mov_b32_e32 v4, v1
	s_waitcnt lgkmcnt(1)
	v_mfma_f32_32x32x16_bf16 v[32:47], v[6:9], v[66:69], v[32:47]
	ds_read_b128 v[66:69], v198 offset:2048
	ds_read_b128 v[70:73], v70 offset:4096
	ds_read_b128 v[74:77], v198 offset:3072
	v_mov_b32_e32 v5, v1
	v_mov_b32_e32 v6, v1
	v_mov_b32_e32 v7, v1
	v_mov_b32_e32 v8, v1
	v_mov_b32_e32 v9, v1
	s_waitcnt lgkmcnt(2)
	v_mfma_f32_32x32x16_bf16 v[48:63], v[10:13], v[66:69], v[48:63]
	v_bitop3_b32 v12, v194, v15, 6 bitop3:0x36
	v_lshl_or_b32 v202, v12, 4, v14
	v_add_u32_e32 v85, s26, v202
	ds_read_b128 v[78:81], v85
	v_mov_b32_e32 v14, v1
	v_mov_b32_e32 v15, v1
	v_mov_b32_e32 v10, v1
	s_waitcnt lgkmcnt(2)
	v_mfma_f32_32x32x16_bf16 v[32:47], v[70:73], v[66:69], v[32:47]
	ds_read_b128 v[66:69], v85 offset:4096
	v_and_b32_e32 v70, 32, v105
	v_and_or_b32 v70, v84, s6, v70
	v_and_b32_e32 v71, 0x100, v82
	v_or3_b32 v196, v70, v71, v83
	s_cselect_b32 s6, 0, 0
	s_lshl_b32 s36, s27, 14
	s_waitcnt lgkmcnt(1)
; __device__ __forceinline__ float max3f(float a, float b, float c) { return __builtin_fmaxf(__builtin_fmaxf(a, b), c); }
; template <bool FIRST, bool MLA>
; __device__ __forceinline__ void partialSM(f32x16& p0, f32x16& p1, f32x16& negm, float& m_reg, float& alpha) {
;   float a = max3f(p0[0], p0[1], p1[0]), b = max3f(p0[2], p0[3], p1[1]); a = max3f(a, p1[2], p1[3]);
; #pragma unroll
;   for (int r = 4; r < 16; r += 4) { a = max3f(a, p0[r], p0[r + 1]); b = max3f(b, p0[r + 2], p0[r + 3]); a = max3f(a, p1[r], p1[r + 1]); b = max3f(b, p1[r + 2], p1[r + 3]); }
;   float pmax = fmaxf(a, b);
;   { auto rr = __builtin_amdgcn_permlane32_swap(__float_as_uint(pmax), __float_as_uint(pmax), false, false);
;     pmax = fmaxf(__uint_as_float(rr[0]), __uint_as_float(rr[1])); }
;   alpha = 1.f;
;   if constexpr (MLA) {
;     if (FIRST) m_reg = pmax;
;     else if (!__builtin_expect(__all(pmax - m_reg <= THR2), 1)) { const float mn = fmaxf(m_reg, pmax); alpha = __builtin_amdgcn_exp2f(m_reg - mn); m_reg = mn; }
; #pragma unroll
;     for (int r = 0; r < 16; ++r) { p0[r] -= m_reg; p1[r] -= m_reg; }
;   } else
;   if (FIRST || __builtin_expect(__any(pmax > THR2), 0)) {
;     const float d = FIRST ? pmax : fmaxf(pmax, 0.f);
; #pragma unroll
;     for (int r = 0; r < 16; ++r) { p0[r] -= d; p1[r] -= d; }
; #pragma unroll
;     for (int r = 0; r < 16; ++r) negm[r] -= d;
;     asm volatile("" : "+v"(negm));
;     if (!FIRST) alpha = __builtin_amdgcn_exp2f(-d);
;   }
; #pragma unroll
;   for (int r = 0; r < 16; ++r) p0[r] = __builtin_amdgcn_exp2f(p0[r]);
	v_mfma_f32_32x32x16_bf16 v[48:63], v[78:81], v[74:77], v[48:63]
	v_mov_b32_e32 v11, v1
	v_mov_b32_e32 v12, v1
	v_mov_b32_e32 v13, v1
	s_mov_b32 s26, -1
	v_add_u32_e32 v197, s6, v196
	v_cmp_gt_u32_e64 s[6:7], 32, v98
	s_waitcnt lgkmcnt(0)
	v_mfma_f32_32x32x16_bf16 v[32:47], v[66:69], v[74:77], v[32:47]
	s_nop 3
	v_max_f32_e32 v66, v49, v49
	v_max_f32_e32 v67, v48, v48
	v_max_f32_e32 v66, v67, v66
	s_nop 4
	v_max3_f32 v67, v50, v51, v33
	v_max3_f32 v66, v66, v32, v34
	v_max3_f32 v66, v66, v35, v52
	v_max3_f32 v67, v67, v54, v55
	v_max3_f32 v66, v66, v53, v36
	v_max3_f32 v67, v67, v38, v39
	v_max3_f32 v66, v66, v37, v56
	v_max3_f32 v67, v67, v58, v59
	v_max3_f32 v66, v66, v57, v40
	v_max3_f32 v67, v67, v42, v43
	v_max3_f32 v66, v66, v41, v60
	v_max3_f32 v67, v67, v62, v63
	v_max3_f32 v66, v66, v61, v44
	v_max3_f32 v67, v67, v46, v47
	v_max3_f32 v66, v66, v45, v67
	v_mov_b32_e32 v67, v66
	s_nop 1
	v_permlane32_swap_b32_e32 v66, v67
	v_max_f32_e32 v67, v67, v67
	v_max_f32_e32 v66, v66, v66
	v_max_f32_e32 v66, v66, v67
	v_sub_f32_e32 v48, v48, v66
	v_sub_f32_e32 v49, v49, v66
	v_sub_f32_e32 v50, v50, v66
	v_sub_f32_e32 v51, v51, v66
	v_sub_f32_e32 v52, v52, v66
	v_sub_f32_e32 v53, v53, v66
	v_sub_f32_e32 v54, v54, v66
	v_sub_f32_e32 v55, v55, v66
	v_sub_f32_e32 v56, v56, v66
	v_sub_f32_e32 v57, v57, v66
	v_sub_f32_e32 v58, v58, v66
	v_sub_f32_e32 v59, v59, v66
	v_sub_f32_e32 v60, v60, v66
	v_sub_f32_e32 v61, v61, v66
	v_sub_f32_e32 v62, v62, v66
	v_sub_f32_e32 v63, v63, v66
	v_sub_f32_e32 v97, v47, v66
	v_sub_f32_e32 v96, v46, v66
	v_sub_f32_e32 v95, v45, v66
	v_sub_f32_e32 v94, v44, v66
	v_sub_f32_e32 v93, v43, v66
	v_sub_f32_e32 v92, v42, v66
	v_sub_f32_e32 v91, v41, v66
	v_sub_f32_e32 v90, v40, v66
	v_sub_f32_e32 v89, v39, v66
	v_sub_f32_e32 v88, v38, v66
	v_sub_f32_e32 v87, v37, v66
	v_sub_f32_e32 v86, v36, v66
	v_sub_f32_e32 v85, v35, v66
	v_sub_f32_e32 v84, v34, v66
	v_sub_f32_e32 v83, v33, v66
	v_sub_f32_e32 v82, v32, v66
	v_sub_f32_e32 v81, v31, v66
	v_sub_f32_e32 v80, v30, v66
	v_sub_f32_e32 v79, v29, v66
	v_sub_f32_e32 v78, v28, v66
	v_sub_f32_e32 v77, v27, v66
	v_sub_f32_e32 v76, v26, v66
	v_sub_f32_e32 v75, v25, v66
	v_sub_f32_e32 v74, v24, v66
	v_sub_f32_e32 v73, v23, v66
	v_sub_f32_e32 v72, v22, v66
	v_sub_f32_e32 v71, v21, v66
	v_sub_f32_e32 v70, v20, v66
	v_sub_f32_e32 v69, v19, v66
	v_sub_f32_e32 v68, v18, v66
	v_sub_f32_e32 v67, v17, v66
	v_sub_f32_e32 v66, v16, v66
	v_lshlrev_b32_e32 v16, 11, v103
	v_or3_b32 v16, s36, v16, v104
	s_load_dwordx4 s[36:39], s[0:1], 0x120
	v_mov_b32_e32 v17, v1
	v_and_b32_e32 v18, 3, v64
	v_lshlrev_b32_e32 v18, 4, v18
	v_exp_f32_e32 v227, v48
	s_waitcnt lgkmcnt(0)
	s_add_u32 s10, s38, s10
	s_addc_u32 s11, s39, s11
	v_lshl_add_u64 v[168:169], s[10:11], 0, v[16:17]
	s_or_b32 s2, s2, s30
	v_or_b32_e32 v16, s31, v100
	v_or3_b32 v16, v16, s34, v99
	s_add_u32 s2, s38, s2
	v_lshlrev_b32_e32 v16, 12, v16
	v_and_b32_e32 v17, 64, v105
	s_addc_u32 s3, s39, s3
	s_lshl_b32 s10, s27, 15
	v_or3_b32 v16, v16, v17, v18
	v_mov_b32_e32 v17, v1
	v_lshl_or_b32 v18, v65, 12, s10
	v_exp_f32_e32 v229, v49
	v_exp_f32_e32 v225, v50
	v_exp_f32_e32 v228, v51
	v_exp_f32_e32 v224, v52
	v_exp_f32_e32 v226, v53
	v_exp_f32_e32 v222, v54
	v_exp_f32_e32 v223, v55
	v_exp_f32_e32 v219, v56
	v_exp_f32_e32 v221, v57
	v_exp_f32_e32 v218, v58
	v_exp_f32_e32 v220, v59
	v_exp_f32_e32 v215, v60
	v_exp_f32_e32 v217, v61
	v_exp_f32_e32 v214, v62
	v_exp_f32_e32 v216, v63
	v_lshl_add_u64 v[170:171], s[2:3], 0, v[16:17]
	v_or_b32_e32 v16, v18, v101
	s_movk_i32 s10, 0x4000
	v_lshl_add_u64 v[172:173], s[2:3], 0, v[16:17]
	v_or3_b32 v16, v18, v102, s10
	v_mov_b64_e32 v[64:65], v[14:15]
	v_mov_b64_e32 v[48:49], v[14:15]
	v_mov_b64_e32 v[32:33], v[14:15]
	v_lshl_add_u64 v[174:175], s[2:3], 0, v[16:17]
	v_mov_b64_e32 v[62:63], v[12:13]
	v_mov_b64_e32 v[60:61], v[10:11]
	v_mov_b64_e32 v[58:59], v[8:9]
	v_mov_b64_e32 v[56:57], v[6:7]
	v_mov_b64_e32 v[54:55], v[4:5]
	v_mov_b64_e32 v[52:53], v[2:3]
	v_mov_b64_e32 v[50:51], v[0:1]
	v_mov_b64_e32 v[46:47], v[12:13]
	v_mov_b64_e32 v[44:45], v[10:11]
	v_mov_b64_e32 v[42:43], v[8:9]
	v_mov_b64_e32 v[40:41], v[6:7]
	v_mov_b64_e32 v[38:39], v[4:5]
	v_mov_b64_e32 v[36:37], v[2:3]
	v_mov_b64_e32 v[34:35], v[0:1]
	v_mov_b64_e32 v[30:31], v[12:13]
	v_mov_b64_e32 v[28:29], v[10:11]
	v_mov_b64_e32 v[26:27], v[8:9]
	v_mov_b64_e32 v[24:25], v[6:7]
	v_mov_b64_e32 v[22:23], v[4:5]
	v_mov_b64_e32 v[20:21], v[2:3]
	v_mov_b64_e32 v[18:19], v[0:1]
	v_mov_b64_e32 v[16:17], v[14:15]
	v_mov_b64_e32 v[14:15], v[12:13]
	v_mov_b64_e32 v[12:13], v[10:11]
	v_mov_b64_e32 v[10:11], v[8:9]
	v_mov_b64_e32 v[8:9], v[6:7]
	v_mov_b64_e32 v[6:7], v[4:5]
	v_mov_b64_e32 v[4:5], v[2:3]
	v_mov_b64_e32 v[2:3], v[0:1]

; #define SBAR() __builtin_amdgcn_sched_barrier(0)
; __device__ __forceinline__ int crow(int r, int hi) { return (r & 3) + 8 * (r >> 2) + 4 * hi; }
; #define RESC(a) do { if (__any((a) < 1.f)) { if (hi == 0) al_l[r32] = (a); asm volatile("s_waitcnt lgkmcnt(0)" ::: "memory"); \
;     _Pragma("unroll") for (int d = 0; d < 4; ++d) _Pragma("unroll") for (int r = 0; r < 16; ++r) o[d][r] *= al_l[crow(r, hi)]; } } while (0)
; __device__ __forceinline__ void finishSM(f32x16& p0, f32x16& p1, float alpha, float& l_reg, bf16x8& pa0, bf16x8& pa1, bf16x8& pa2, bf16x8& pa3) {
; #pragma unroll
;   for (int r = 0; r < 16; ++r) p1[r] = __builtin_amdgcn_exp2f(p1[r]);
;   float ps = 0;
; #pragma unroll
;   for (int r = 0; r < 16; ++r) ps += p0[r];
; #pragma unroll
;   for (int r = 0; r < 16; ++r) ps += p1[r];
;   { auto rr = __builtin_amdgcn_permlane32_swap(__float_as_uint(ps), __float_as_uint(ps), false, false);
;     ps = __uint_as_float(rr[0]) + __uint_as_float(rr[1]); }
;   l_reg = l_reg * alpha + ps;
;     ...
;   PK4(p0, 0, pa0); PK4(p0, 8, pa1); PK4(p1, 0, pa2); PK4(p1, 8, pa3);
; template <bool MLA> ...
;     ...
;   RESC(alB);
;   finishSM(pB0, pB1, alB, l_reg, pa0, pa1, pa2, pa3); SBAR();
;   pv_d0(o, vb0 + s_cur * SHM_V, pa0, pa1, pa2, pa3);
;   if (hi == 0) li_l[r32] = l_reg; asm volatile("s_waitcnt lgkmcnt(0)" ::: "memory");
;   float rli[16];
; #pragma unroll
;   for (int r = 0; r < 16; ++r) rli[r] = __builtin_amdgcn_rcpf(li_l[crow(r, hi)]);
.LBB0_121:
	v_exp_f32_e32 v68, v114
	v_exp_f32_e32 v69, v115
	v_exp_f32_e32 v70, v116
	v_exp_f32_e32 v71, v117
	v_exp_f32_e32 v72, v118
	v_add_f32_e32 v66, 0, v68
	v_exp_f32_e32 v73, v119
	v_add_f32_e32 v66, v69, v66
	v_exp_f32_e32 v74, v120
	v_add_f32_e32 v66, v70, v66
	v_exp_f32_e32 v75, v121
	v_add_f32_e32 v66, v71, v66
	v_exp_f32_e32 v76, v122
	v_add_f32_e32 v66, v72, v66
	v_exp_f32_e32 v77, v123
	v_add_f32_e32 v66, v73, v66
	v_exp_f32_e32 v78, v124
	v_add_f32_e32 v66, v74, v66
	v_exp_f32_e32 v79, v125
	v_add_f32_e32 v66, v75, v66
	v_exp_f32_e32 v80, v126
	v_add_f32_e32 v66, v76, v66
	v_exp_f32_e32 v81, v127
	v_add_f32_e32 v66, v77, v66
	v_exp_f32_e32 v84, v128
	v_add_f32_e32 v66, v78, v66
	v_exp_f32_e32 v85, v129
	v_add_f32_e32 v66, v79, v66
	v_exp_f32_e32 v86, v98
	v_add_f32_e32 v66, v80, v66
	v_exp_f32_e32 v87, v99
	v_add_f32_e32 v66, v81, v66
	v_exp_f32_e32 v88, v100
	v_add_f32_e32 v66, v84, v66
	v_exp_f32_e32 v89, v101
	v_add_f32_e32 v66, v85, v66
	v_exp_f32_e32 v90, v102
	v_add_f32_e32 v66, v86, v66
	v_exp_f32_e32 v91, v103
	v_add_f32_e32 v66, v87, v66
	v_exp_f32_e32 v92, v104
	v_add_f32_e32 v66, v88, v66
	v_exp_f32_e32 v93, v105
	v_add_f32_e32 v66, v89, v66
	v_exp_f32_e32 v94, v106
	v_add_f32_e32 v66, v90, v66
	v_exp_f32_e32 v95, v107
	v_add_f32_e32 v66, v91, v66
	v_exp_f32_e32 v96, v108
	v_add_f32_e32 v66, v92, v66
	v_exp_f32_e32 v97, v109
	v_add_f32_e32 v66, v93, v66
	v_exp_f32_e32 v98, v110
	v_add_f32_e32 v66, v94, v66
	v_exp_f32_e32 v99, v111
	v_add_f32_e32 v66, v95, v66
	v_exp_f32_e32 v100, v112
	v_add_f32_e32 v66, v96, v66
	v_exp_f32_e32 v101, v113
	v_add_f32_e32 v66, v97, v66
	v_add_f32_e32 v66, v98, v66
	v_add_f32_e32 v66, v99, v66
	v_add_f32_e32 v66, v100, v66
	v_add_f32_e32 v66, v101, v66
	v_mov_b32_e32 v67, v66
	s_nop 1
	v_permlane32_swap_b32_e32 v66, v67
	v_cvt_pk_bf16_f32 v68, v68, v69
	v_cvt_pk_bf16_f32 v69, v70, v71
	v_cvt_pk_bf16_f32 v70, v72, v73
	v_cvt_pk_bf16_f32 v71, v74, v75
	v_cvt_pk_bf16_f32 v72, v76, v77
	v_cvt_pk_bf16_f32 v73, v78, v79
	v_cvt_pk_bf16_f32 v74, v80, v81
	v_cvt_pk_bf16_f32 v75, v84, v85
	v_cvt_pk_bf16_f32 v76, v86, v87
	v_cvt_pk_bf16_f32 v77, v88, v89
	v_cvt_pk_bf16_f32 v78, v90, v91
	v_cvt_pk_bf16_f32 v79, v92, v93
	v_cvt_pk_bf16_f32 v84, v94, v95
	v_cvt_pk_bf16_f32 v85, v96, v97
	v_cvt_pk_bf16_f32 v86, v98, v99
	v_cvt_pk_bf16_f32 v87, v100, v101
	s_nop 0
	v_permlane32_swap_b32_e32 v68, v70
	v_permlane32_swap_b32_e32 v69, v71
	v_permlane32_swap_b32_e32 v72, v74
	v_permlane32_swap_b32_e32 v73, v75
	v_permlane32_swap_b32_e32 v76, v78
	v_permlane32_swap_b32_e32 v77, v79
	v_permlane32_swap_b32_e32 v84, v86
	v_permlane32_swap_b32_e32 v85, v87
	s_cmp_lg_u32 0, -1
	s_cselect_b32 s2, 0, 0
	s_addk_i32 s2, 0x4000
	v_add_u32_e32 v80, s2, v196
	ds_read_b64_tr_b16 v[88:89], v80 offset:0
	ds_read_b64_tr_b16 v[90:91], v80 offset:0x800
	ds_read_b64_tr_b16 v[92:93], v80 offset:0x1000
	ds_read_b64_tr_b16 v[94:95], v80 offset:0x1800
	ds_read_b64_tr_b16 v[96:97], v80 offset:0x2000
	ds_read_b64_tr_b16 v[98:99], v80 offset:0x2800
	ds_read_b64_tr_b16 v[100:101], v80 offset:0x3000
	ds_read_b64_tr_b16 v[102:103], v80 offset:0x3800
	s_waitcnt lgkmcnt(0)
	s_nop 0
	v_mfma_f32_32x32x16_bf16 v[50:65], v[68:71], v[88:91], v[50:65]
	ds_read_b64_tr_b16 v[88:89], v80 offset:0x200
	ds_read_b64_tr_b16 v[90:91], v80 offset:0xa00
	v_mfma_f32_32x32x16_bf16 v[50:65], v[72:75], v[92:95], v[50:65]
	ds_read_b64_tr_b16 v[92:93], v80 offset:0x1200
	ds_read_b64_tr_b16 v[94:95], v80 offset:0x1a00
	v_mfma_f32_32x32x16_bf16 v[50:65], v[76:79], v[96:99], v[50:65]
	ds_read_b64_tr_b16 v[96:97], v80 offset:0x2200
	ds_read_b64_tr_b16 v[98:99], v80 offset:0x2a00
	v_mfma_f32_32x32x16_bf16 v[50:65], v[84:87], v[100:103], v[50:65]
	ds_read_b64_tr_b16 v[100:101], v80 offset:0x3200
	ds_read_b64_tr_b16 v[102:103], v80 offset:0x3a00
	s_waitcnt lgkmcnt(0)
	v_mfma_f32_32x32x16_bf16 v[34:49], v[68:71], v[88:91], v[34:49]
	ds_read_b64_tr_b16 v[88:89], v80 offset:0x400
	ds_read_b64_tr_b16 v[90:91], v80 offset:0xc00
	v_mfma_f32_32x32x16_bf16 v[34:49], v[72:75], v[92:95], v[34:49]
	ds_read_b64_tr_b16 v[92:93], v80 offset:0x1400
	ds_read_b64_tr_b16 v[94:95], v80 offset:0x1c00
	v_mfma_f32_32x32x16_bf16 v[34:49], v[76:79], v[96:99], v[34:49]
	ds_read_b64_tr_b16 v[96:97], v80 offset:0x2400
	ds_read_b64_tr_b16 v[98:99], v80 offset:0x2c00
	v_mfma_f32_32x32x16_bf16 v[34:49], v[84:87], v[100:103], v[34:49]
	ds_read_b64_tr_b16 v[100:101], v80 offset:0x3400
	ds_read_b64_tr_b16 v[102:103], v80 offset:0x3c00
	s_waitcnt lgkmcnt(0)
	v_mfma_f32_32x32x16_bf16 v[18:33], v[68:71], v[88:91], v[18:33]
	ds_read_b64_tr_b16 v[88:89], v80 offset:0x600
	ds_read_b64_tr_b16 v[90:91], v80 offset:0xe00
	v_mfma_f32_32x32x16_bf16 v[18:33], v[72:75], v[92:95], v[18:33]
	ds_read_b64_tr_b16 v[92:93], v80 offset:0x1600
	ds_read_b64_tr_b16 v[94:95], v80 offset:0x1e00
	v_mfma_f32_32x32x16_bf16 v[18:33], v[76:79], v[96:99], v[18:33]
	ds_read_b64_tr_b16 v[96:97], v80 offset:0x2600
	ds_read_b64_tr_b16 v[98:99], v80 offset:0x2e00
	v_mfma_f32_32x32x16_bf16 v[18:33], v[84:87], v[100:103], v[18:33]
	ds_read_b64_tr_b16 v[100:101], v80 offset:0x3600
	ds_read_b64_tr_b16 v[102:103], v80 offset:0x3e00
	s_waitcnt lgkmcnt(0)
	v_mfma_f32_32x32x16_bf16 v[2:17], v[68:71], v[88:91], v[2:17]
	v_mfma_f32_32x32x16_bf16 v[2:17], v[72:75], v[92:95], v[2:17]
	v_mfma_f32_32x32x16_bf16 v[2:17], v[76:79], v[96:99], v[2:17]
	v_mfma_f32_32x32x16_bf16 v[2:17], v[84:87], v[100:103], v[2:17]
	s_and_saveexec_b64 s[2:3], s[6:7]
	v_add_f32_e32 v0, v0, v82
	v_fmac_f32_e32 v0, v195, v176
	v_add_f32_e32 v66, v66, v67
	v_fmac_f32_e32 v66, v0, v83
	ds_write_b32 v167, v66
	s_or_b64 exec, exec, s[2:3]
	s_waitcnt lgkmcnt(0)
	v_add_u32_e32 v0, s9, v166
	ds_read_b128 v[66:69], v0
	ds_read_b128 v[70:73], v0 offset:32
	ds_read_b128 v[74:77], v0 offset:64
	ds_read_b128 v[78:81], v0 offset:96
	s_mul_hi_i32 s3, s14, 0x1800
	s_mulk_i32 s14, 0x1800
	s_add_u32 s2, s4, s14
	s_addc_u32 s3, s5, s3
	v_and_b32_e32 v83, 0x1c0, v184
	v_lshlrev_b32_e32 v83, 7, v83
	v_and_b32_e32 v82, 32, v184
	v_lshl_or_b32 v83, v82, 5, v83
	v_and_b32_e32 v82, 31, v184
	v_lshl_or_b32 v83, v82, 1, v83
	s_waitcnt lgkmcnt(0)
	s_barrier
; __device__ __forceinline__ unsigned cvt_pk_bf16(float lo, float hi) { unsigned r; asm volatile("v_cvt_pk_bf16_f32 %0, %1, %2" : "=v"(r) : "v"(lo), "v"(hi)); return r; }
; __device__ __forceinline__ int crow(int r, int hi) { return (r & 3) + 8 * (r >> 2) + 4 * hi; }
; template <bool MLA> ...
;     ...
;   float rli[16];
; #pragma unroll
;   for (int r = 0; r < 16; ++r) rli[r] = __builtin_amdgcn_rcpf(li_l[crow(r, hi)]);
;   bf16_t* Ow = Ob + (long)(wid * QBLK) * LDO;
; #pragma unroll
;   for (int r = 0; r < 16; ++r) { int orow = crow(r, hi);
; #pragma unroll
;     for (int d0 = 0; d0 < 4; ++d0) Ow[(long)orow * LDO + d0 * 32 + r32] = (bf16_t)(cvt_pk_bf16(o[d0][r] * rli[r], 0.f) & 0xffffu); }
	v_rcp_f32_e32 v66, v66
	v_rcp_f32_e32 v67, v67
	v_rcp_f32_e32 v68, v68
	v_rcp_f32_e32 v69, v69
	v_rcp_f32_e32 v70, v70
	v_rcp_f32_e32 v71, v71
	v_rcp_f32_e32 v72, v72
	v_rcp_f32_e32 v73, v73
	v_rcp_f32_e32 v74, v74
	v_rcp_f32_e32 v75, v75
	v_rcp_f32_e32 v76, v76
	v_rcp_f32_e32 v77, v77
	v_rcp_f32_e32 v78, v78
	v_rcp_f32_e32 v79, v79
	v_rcp_f32_e32 v80, v80
	v_rcp_f32_e32 v81, v81
	s_nop 0
	v_mul_f32_e32 v82, v50, v66
	v_cvt_pk_bf16_f32 v82, v82, v1
	ds_write_b16 v83, v82 offset:0
	v_mul_f32_e32 v0, v34, v66
	v_cvt_pk_bf16_f32 v0, v0, v1
	ds_write_b16 v83, v0 offset:64
	v_mul_f32_e32 v82, v18, v66
	v_cvt_pk_bf16_f32 v82, v82, v1
	ds_write_b16 v83, v82 offset:128
	v_mul_f32_e32 v0, v2, v66
	v_cvt_pk_bf16_f32 v0, v0, v1
	ds_write_b16 v83, v0 offset:192
	v_mul_f32_e32 v82, v51, v67
	v_cvt_pk_bf16_f32 v82, v82, v1
	ds_write_b16 v83, v82 offset:256
	v_mul_f32_e32 v0, v35, v67
	v_cvt_pk_bf16_f32 v0, v0, v1
	ds_write_b16 v83, v0 offset:320
	v_mul_f32_e32 v82, v19, v67
	v_cvt_pk_bf16_f32 v82, v82, v1
	ds_write_b16 v83, v82 offset:384
	v_mul_f32_e32 v0, v3, v67
	v_cvt_pk_bf16_f32 v0, v0, v1
	ds_write_b16 v83, v0 offset:448
	v_mul_f32_e32 v82, v52, v68
	v_cvt_pk_bf16_f32 v82, v82, v1
	ds_write_b16 v83, v82 offset:512
	v_mul_f32_e32 v0, v36, v68
	v_cvt_pk_bf16_f32 v0, v0, v1
	ds_write_b16 v83, v0 offset:576
	v_mul_f32_e32 v82, v20, v68
	v_cvt_pk_bf16_f32 v82, v82, v1
	ds_write_b16 v83, v82 offset:640
	v_mul_f32_e32 v0, v4, v68
	v_cvt_pk_bf16_f32 v0, v0, v1
	ds_write_b16 v83, v0 offset:704
	v_mul_f32_e32 v82, v53, v69
	v_cvt_pk_bf16_f32 v82, v82, v1
	ds_write_b16 v83, v82 offset:768
	v_mul_f32_e32 v0, v37, v69
	v_cvt_pk_bf16_f32 v0, v0, v1
	ds_write_b16 v83, v0 offset:832
	v_mul_f32_e32 v82, v21, v69
	v_cvt_pk_bf16_f32 v82, v82, v1
	ds_write_b16 v83, v82 offset:896
	v_mul_f32_e32 v0, v5, v69
	v_cvt_pk_bf16_f32 v0, v0, v1
	ds_write_b16 v83, v0 offset:960
	v_mul_f32_e32 v82, v54, v70
	v_cvt_pk_bf16_f32 v82, v82, v1
	ds_write_b16 v83, v82 offset:2048
	v_mul_f32_e32 v0, v38, v70
	v_cvt_pk_bf16_f32 v0, v0, v1
	ds_write_b16 v83, v0 offset:2112
	v_mul_f32_e32 v82, v22, v70
	v_cvt_pk_bf16_f32 v82, v82, v1
	ds_write_b16 v83, v82 offset:2176
	v_mul_f32_e32 v0, v6, v70
	v_cvt_pk_bf16_f32 v0, v0, v1
	ds_write_b16 v83, v0 offset:2240
	v_mul_f32_e32 v82, v55, v71
	v_cvt_pk_bf16_f32 v82, v82, v1
	ds_write_b16 v83, v82 offset:2304
	v_mul_f32_e32 v0, v39, v71
	v_cvt_pk_bf16_f32 v0, v0, v1
	ds_write_b16 v83, v0 offset:2368
	v_mul_f32_e32 v82, v23, v71
	v_cvt_pk_bf16_f32 v82, v82, v1
	ds_write_b16 v83, v82 offset:2432
	v_mul_f32_e32 v0, v7, v71
	v_cvt_pk_bf16_f32 v0, v0, v1
	ds_write_b16 v83, v0 offset:2496
	v_mul_f32_e32 v82, v56, v72
	v_cvt_pk_bf16_f32 v82, v82, v1
	ds_write_b16 v83, v82 offset:2560
	v_mul_f32_e32 v0, v40, v72
	v_cvt_pk_bf16_f32 v0, v0, v1
	ds_write_b16 v83, v0 offset:2624
	v_mul_f32_e32 v82, v24, v72
	v_cvt_pk_bf16_f32 v82, v82, v1
	ds_write_b16 v83, v82 offset:2688
	v_mul_f32_e32 v0, v8, v72
	v_cvt_pk_bf16_f32 v0, v0, v1
	ds_write_b16 v83, v0 offset:2752
	v_mul_f32_e32 v82, v57, v73
	v_cvt_pk_bf16_f32 v82, v82, v1
	ds_write_b16 v83, v82 offset:2816
	v_mul_f32_e32 v0, v41, v73
	v_cvt_pk_bf16_f32 v0, v0, v1
	ds_write_b16 v83, v0 offset:2880
	v_mul_f32_e32 v82, v25, v73
	v_cvt_pk_bf16_f32 v82, v82, v1
	ds_write_b16 v83, v82 offset:2944
	v_mul_f32_e32 v0, v9, v73
	v_cvt_pk_bf16_f32 v0, v0, v1
	ds_write_b16 v83, v0 offset:3008
	v_mul_f32_e32 v82, v58, v74
	v_cvt_pk_bf16_f32 v82, v82, v1
	ds_write_b16 v83, v82 offset:4096
	v_mul_f32_e32 v0, v42, v74
	v_cvt_pk_bf16_f32 v0, v0, v1
	ds_write_b16 v83, v0 offset:4160
	v_mul_f32_e32 v82, v26, v74
	v_cvt_pk_bf16_f32 v82, v82, v1
	ds_write_b16 v83, v82 offset:4224
	v_mul_f32_e32 v0, v10, v74
	v_cvt_pk_bf16_f32 v0, v0, v1
	ds_write_b16 v83, v0 offset:4288
	v_mul_f32_e32 v82, v59, v75
	v_cvt_pk_bf16_f32 v82, v82, v1
	ds_write_b16 v83, v82 offset:4352
	v_mul_f32_e32 v0, v43, v75
	v_cvt_pk_bf16_f32 v0, v0, v1
	ds_write_b16 v83, v0 offset:4416
	v_mul_f32_e32 v82, v27, v75
	v_cvt_pk_bf16_f32 v82, v82, v1
	ds_write_b16 v83, v82 offset:4480
	v_mul_f32_e32 v0, v11, v75
	v_cvt_pk_bf16_f32 v0, v0, v1
	ds_write_b16 v83, v0 offset:4544
	v_mul_f32_e32 v82, v60, v76
	v_cvt_pk_bf16_f32 v82, v82, v1
	ds_write_b16 v83, v82 offset:4608
	v_mul_f32_e32 v0, v44, v76
	v_cvt_pk_bf16_f32 v0, v0, v1
	ds_write_b16 v83, v0 offset:4672
	v_mul_f32_e32 v82, v28, v76
	v_cvt_pk_bf16_f32 v82, v82, v1
	ds_write_b16 v83, v82 offset:4736
	v_mul_f32_e32 v0, v12, v76
	v_cvt_pk_bf16_f32 v0, v0, v1
	ds_write_b16 v83, v0 offset:4800
	v_mul_f32_e32 v82, v61, v77
	v_cvt_pk_bf16_f32 v82, v82, v1
	ds_write_b16 v83, v82 offset:4864
	v_mul_f32_e32 v0, v45, v77
	v_cvt_pk_bf16_f32 v0, v0, v1
	ds_write_b16 v83, v0 offset:4928
	v_mul_f32_e32 v82, v29, v77
	v_cvt_pk_bf16_f32 v82, v82, v1
	ds_write_b16 v83, v82 offset:4992
	v_mul_f32_e32 v0, v13, v77
	v_cvt_pk_bf16_f32 v0, v0, v1
	ds_write_b16 v83, v0 offset:5056
	v_mul_f32_e32 v82, v62, v78
	v_cvt_pk_bf16_f32 v82, v82, v1
	ds_write_b16 v83, v82 offset:6144
	v_mul_f32_e32 v0, v46, v78
	v_cvt_pk_bf16_f32 v0, v0, v1
	ds_write_b16 v83, v0 offset:6208
	v_mul_f32_e32 v82, v30, v78
	v_cvt_pk_bf16_f32 v82, v82, v1
	ds_write_b16 v83, v82 offset:6272
	v_mul_f32_e32 v0, v14, v78
	v_cvt_pk_bf16_f32 v0, v0, v1
	ds_write_b16 v83, v0 offset:6336
	v_mul_f32_e32 v82, v63, v79
	v_cvt_pk_bf16_f32 v82, v82, v1
	ds_write_b16 v83, v82 offset:6400
	v_mul_f32_e32 v0, v47, v79
	v_cvt_pk_bf16_f32 v0, v0, v1
	ds_write_b16 v83, v0 offset:6464
	v_mul_f32_e32 v82, v31, v79
	v_cvt_pk_bf16_f32 v82, v82, v1
	ds_write_b16 v83, v82 offset:6528
	v_mul_f32_e32 v0, v15, v79
	v_cvt_pk_bf16_f32 v0, v0, v1
	ds_write_b16 v83, v0 offset:6592
	v_mul_f32_e32 v82, v64, v80
	v_cvt_pk_bf16_f32 v82, v82, v1
	ds_write_b16 v83, v82 offset:6656
	v_mul_f32_e32 v0, v48, v80
	v_cvt_pk_bf16_f32 v0, v0, v1
	ds_write_b16 v83, v0 offset:6720
	v_mul_f32_e32 v82, v32, v80
	v_cvt_pk_bf16_f32 v82, v82, v1
	ds_write_b16 v83, v82 offset:6784
	v_mul_f32_e32 v0, v16, v80
	v_cvt_pk_bf16_f32 v0, v0, v1
	ds_write_b16 v83, v0 offset:6848
	v_mul_f32_e32 v82, v65, v81
	v_cvt_pk_bf16_f32 v82, v82, v1
	ds_write_b16 v83, v82 offset:6912
	v_mul_f32_e32 v0, v49, v81
	v_cvt_pk_bf16_f32 v0, v0, v1
	ds_write_b16 v83, v0 offset:6976
	v_mul_f32_e32 v82, v33, v81
	v_cvt_pk_bf16_f32 v82, v82, v1
	ds_write_b16 v83, v82 offset:7040
	v_mul_f32_e32 v0, v17, v81
	v_cvt_pk_bf16_f32 v0, v0, v1
	ds_write_b16 v83, v0 offset:7104
	s_waitcnt lgkmcnt(0)
; __device__ __forceinline__ unsigned cvt_pk_bf16(float lo, float hi) { unsigned r; asm volatile("v_cvt_pk_bf16_f32 %0, %1, %2" : "=v"(r) : "v"(lo), "v"(hi)); return r; }
; __device__ __forceinline__ int opaque_tid() { int t = threadIdx.x; asm volatile("" : "+v"(t)); return t; }
; __device__ __forceinline__ int crow(int r, int hi) { return (r & 3) + 8 * (r >> 2) + 4 * hi; }
; template <bool MLA> ...
;     ...
;   const int tid = opaque_tid(), wid = __builtin_amdgcn_readfirstlane(tid >> 6), lane = tid & 63, r32 = lane & 31, hi = lane >> 5;
;   char* V_lds = lds + OFF_V; char* K_lds = lds + OFF_K; char* KR_lds = lds + OFF_KR;
;   float* ws = (float*)(lds + OFF_WS) + wid * 64; float* li_l = ws; float* al_l = ws + 32;
;   unsigned koff[2], voff[2], kroff = 0;
; #pragma unroll
;   for (int i = 0; i < 2; ++i) { const int p = 2 * wid + i;
;     { const int row = 4 * p + (lane >> 4), pc = lane & 15, c = pc ^ (row & 7); koff[i] = (unsigned)(row * LDK + c * 8) * 2u; }
;     { const int o = p * 1024 + lane * 16, sub = o >> 9, w_ = (o & 511) >> 1, kk = (sub >> 2) * 8 + (w_ >> 5), k = (kk & ~0xC) | ((kk & 4) << 1) | ((kk & 8) >> 1), c = (sub & 3) * 32 + (w_ & 31);
;       voff[i] = (unsigned)(k * LDK + c) * 2u; } }
;   if constexpr (MLA) { const int row = 8 * wid + (lane >> 3), pc = lane & 7, ch = pc ^ ((row >> 1) & 7); kroff = (unsigned)(row * LDKR + ch * 8) * 2u; }
;     ...
;   DMA_TILE(0, 0); DMA_TILE(1, 1);
;   float l_reg = 0, m_reg = 0; f32x16 o[4] = {}; bf16x8 qr[8]; f32x16 negm = {}; asm volatile("" : "+v"(negm));
;   char* qrl = lds + OFF_QR + wid * 4096 + lane * 16;
;   { const bf16_t* Qw = Qb + (long)(wid * QBLK + r32) * LDQ + hi * 8;
; #pragma unroll
;     for (int d0 = 0; d0 < 8; ++d0) qr[d0] = *reinterpret_cast<const bf16x8*>(Qw + d0 * 16);
;     if constexpr (MLA) { const bf16_t* Qw2 = Qrb + (long)(wid * QBLK + r32) * LDQ + hi * 8;
; #pragma unroll
;       for (int d0 = 0; d0 < 4; ++d0) *reinterpret_cast<bf16x8*>(qrl + d0 * 1024) = *reinterpret_cast<const bf16x8*>(Qw2 + d0 * 16); } }
;     ...
;   bf16_t* Ow = Ob + (long)(wid * QBLK) * LDO;
; #pragma unroll
;   for (int r = 0; r < 16; ++r) { int orow = crow(r, hi);
; #pragma unroll
;     for (int d0 = 0; d0 < 4; ++d0) Ow[(long)orow * LDO + d0 * 32 + r32] = (bf16_t)(cvt_pk_bf16(o[d0][r] * rli[r], 0.f) & 0xffffu); }
;   __syncthreads();
	v_and_b32_e32 v2, 0x1c0, v184
	v_lshlrev_b32_e32 v2, 7, v2
	v_and_b32_e32 v3, 63, v184
	v_lshl_or_b32 v2, v3, 4, v2
	ds_read_b128 v[4:7], v2 offset:0
	ds_read_b128 v[8:11], v2 offset:1024
	ds_read_b128 v[12:15], v2 offset:2048
	ds_read_b128 v[16:19], v2 offset:3072
	ds_read_b128 v[20:23], v2 offset:4096
	ds_read_b128 v[24:27], v2 offset:5120
	ds_read_b128 v[28:31], v2 offset:6144
	ds_read_b128 v[32:35], v2 offset:7168
	v_bfe_u32 v36, v184, 4, 2
	v_mul_u32_u24_e32 v36, 0x1800, v36
	v_and_b32_e32 v37, 15, v184
	v_lshl_or_b32 v36, v37, 4, v36
	v_mov_b32_e32 v37, 0
	v_lshl_add_u64 v[38:39], s[2:3], 0, v[36:37]
	s_mov_b64 vcc, 0x6000
	v_lshl_add_u64 v[40:41], v[38:39], 0, vcc
	v_lshl_add_u64 v[42:43], v[40:41], 0, vcc
	v_lshl_add_u64 v[44:45], v[42:43], 0, vcc
	v_lshl_add_u64 v[46:47], v[44:45], 0, vcc
	v_lshl_add_u64 v[48:49], v[46:47], 0, vcc
	v_lshl_add_u64 v[50:51], v[48:49], 0, vcc
	v_lshl_add_u64 v[52:53], v[50:51], 0, vcc
	s_waitcnt lgkmcnt(7)
	global_store_dwordx4 v[38:39], v[4:7], off offset:2048
	s_waitcnt lgkmcnt(6)
	global_store_dwordx4 v[40:41], v[8:11], off offset:2048
	s_waitcnt lgkmcnt(5)
	global_store_dwordx4 v[42:43], v[12:15], off offset:2048
	s_waitcnt lgkmcnt(4)
	global_store_dwordx4 v[44:45], v[16:19], off offset:2048
	s_waitcnt lgkmcnt(3)
	global_store_dwordx4 v[46:47], v[20:23], off offset:2048
	s_waitcnt lgkmcnt(2)
	global_store_dwordx4 v[48:49], v[24:27], off offset:2048
	s_waitcnt lgkmcnt(1)
	global_store_dwordx4 v[50:51], v[28:31], off offset:2048
	s_waitcnt lgkmcnt(0)
	global_store_dwordx4 v[52:53], v[32:35], off offset:2048
	s_setprio 0
	s_waitcnt vmcnt(63) expcnt(7) lgkmcnt(15)
	s_barrier
	s_branch .LBB0_98
.LBB0_124:
	s_lshl_b32 s2, s16, 8
	s_add_u32 s4, s17, s2
	s_addc_u32 s5, s18, 0
	s_mul_i32 s2, s8, 0x3000000
	s_mul_hi_i32 s3, s8, 0x3000000
	s_add_u32 s6, s92, s2
	s_addc_u32 s7, s93, s3
	s_lshl_b32 s8, s16, 6
	s_and_b32 s8, s8, 0x100
	s_add_u32 s6, s6, s8
	s_addc_u32 s7, s7, 0
	v_mov_b32_e32 v74, v184
	s_add_u32 s16, s6, 0x1400
	s_addc_u32 s17, s7, 0
	v_readfirstlane_b32 s9, v74
	s_ashr_i32 s8, s9, 6
	s_cmp_lt_u32 s8, 4
	s_cbranch_scc1 .Lprio_skip_gqa
	s_setprio 1
.Lprio_skip_gqa:
	s_and_b32 s9, s9, 0x3fffffc0
	s_lshl_b32 s9, s9, 2
	s_lshl_b32 s11, s8, 3
	v_lshrrev_b32_e32 v0, 1, v74
	s_add_i32 s10, s9, 0
	v_bfe_u32 v99, v74, 4, 2
	v_bfe_u32 v100, v74, 2, 2
	s_and_b32 s9, s11, 0x7ffffff0
	v_and_b32_e32 v101, 8, v0
	s_lshl_b32 s14, s8, 2
	v_and_b32_e32 v98, 63, v74
	s_and_b32 s19, s14, 4
	v_or3_b32 v0, v101, v100, s9
	s_waitcnt vmcnt(0)
	v_or_b32_e32 v3, s11, v99
	v_bitop3_b32 v4, v99, v74, 15 bitop3:0x78
	v_lshlrev_b32_e32 v75, 3, v98
	v_or_b32_e32 v0, s19, v0
	s_movk_i32 s26, 0xc00
	v_lshlrev_b32_e32 v104, 4, v4
	s_and_b32 s32, s8, 1
	s_lshl_b32 s32, s32, 7
	v_xor_b32_e32 v104, s32, v104
	v_mul_lo_u32 v3, v3, s33
	v_and_b32_e32 v2, 15, v74
	v_and_b32_e32 v102, 32, v74
	v_and_b32_e32 v103, 24, v75
	v_mul_lo_u32 v0, v0, s26
	v_or_b32_e32 v6, v3, v104
	v_or_b32_e32 v3, 4, v99
	v_or3_b32 v0, v0, v102, v103
	v_or_b32_e32 v3, s11, v3
	v_bitop3_b32 v2, v99, v2, 4 bitop3:0x36
	s_lshl_b32 s14, s8, 11
	v_lshlrev_b32_e32 v0, 1, v0
	v_lshlrev_b32_e32 v105, 4, v2
	v_xor_b32_e32 v105, s32, v105
	v_mul_lo_u32 v2, v3, s33
	s_add_i32 s15, s14, 0
	v_or_b32_e32 v7, v105, v2
	s_add_i32 m0, s15, 0xc000
	v_lshl_add_u64 v[2:3], s[6:7], 0, v[0:1]
	s_mov_b64 s[24:25], 0x1600
	global_load_lds_dwordx4 v6, s[16:17]
	v_lshl_add_u64 v[4:5], v[2:3], 0, s[24:25]
	s_mov_b32 m0, s15
	s_add_i32 s10, s10, 0x1e000
	global_load_lds_dwordx4 v[4:5], off
	s_add_i32 m0, s15, 0xc400
	v_or_b32_e32 v8, 0x80, v0
	global_load_lds_dwordx4 v7, s[16:17]
	s_mov_b64 s[16:17], 0x1680
	s_add_i32 m0, s15, 0x400
	v_lshl_add_u64 v[2:3], v[2:3], 0, s[16:17]
	s_add_u32 s16, s6, 0x61400
	s_addc_u32 s17, s7, 0
	s_add_u32 s6, s6, 0x61600
	global_load_lds_dwordx4 v[2:3], off
	s_addc_u32 s7, s7, 0
	s_add_i32 m0, s15, 0x10000
	v_mov_b32_e32 v14, v1
	global_load_lds_dwordx4 v6, s[16:17]
	s_add_i32 m0, s15, 0x4000
	v_mov_b32_e32 v15, v1
	global_load_lds_dwordx4 v0, s[6:7]
	s_add_i32 m0, s15, 0x10400
	v_and_b32_e32 v178, 31, v74
	global_load_lds_dwordx4 v7, s[16:17]
	s_add_i32 m0, s15, 0x4400
	v_mov_b32_e32 v0, v1
	global_load_lds_dwordx4 v8, s[6:7]
	v_mov_b32_e32 v2, v1
	v_mov_b32_e32 v3, v1
	v_mov_b32_e32 v4, v1
	v_mov_b32_e32 v5, v1
	v_mov_b32_e32 v6, v1
	v_mov_b32_e32 v7, v1
	v_mov_b32_e32 v8, v1
	v_mov_b32_e32 v9, v1
	v_mov_b32_e32 v10, v1
	v_mov_b32_e32 v11, v1
	v_mov_b32_e32 v12, v1
	v_mov_b32_e32 v13, v1
	v_mov_b64_e32 v[32:33], v[14:15]
	s_lshl_b32 s11, s8, 5
	v_bfe_u32 v179, v74, 5, 1
	v_mov_b64_e32 v[30:31], v[12:13]
	v_mov_b64_e32 v[28:29], v[10:11]
	v_mov_b64_e32 v[26:27], v[8:9]
	v_mov_b64_e32 v[24:25], v[6:7]
	v_mov_b64_e32 v[22:23], v[4:5]
	v_mov_b64_e32 v[20:21], v[2:3]
	v_mov_b64_e32 v[18:19], v[0:1]
	v_or_b32_e32 v0, s11, v178
	v_mov_b64_e32 v[2:3], s[4:5]
	v_mad_i64_i32 v[2:3], s[6:7], v0, s33, v[2:3]
	v_lshlrev_b32_e32 v166, 4, v179
	v_mov_b32_e32 v167, v1
	v_lshl_add_u64 v[2:3], v[2:3], 0, v[166:167]
	global_load_dwordx4 v[158:161], v[2:3], off
	global_load_dwordx4 v[154:157], v[2:3], off offset:32
	global_load_dwordx4 v[150:153], v[2:3], off offset:64
	global_load_dwordx4 v[146:149], v[2:3], off offset:96
	global_load_dwordx4 v[142:145], v[2:3], off offset:128
	global_load_dwordx4 v[138:141], v[2:3], off offset:160
	global_load_dwordx4 v[134:137], v[2:3], off offset:192
	global_load_dwordx4 v[130:133], v[2:3], off offset:224
	v_lshlrev_b32_e32 v0, 4, v74
	v_lshlrev_b32_e32 v13, 8, v178
	v_and_b32_e32 v70, 0xf0, v0
	v_bitop3_b32 v199, v166, v13, v70 bitop3:0xde
	v_add_u32_e32 v6, 0, v199
	s_waitcnt vmcnt(0)
	s_waitcnt vmcnt(0) lgkmcnt(0)
	s_barrier
; #define WAIT_BAR() do { asm volatile("s_waitcnt vmcnt(0)" ::: "memory"); __syncthreads(); } while (0)
; template <bool MLA>
; __device__ __forceinline__ void qkt(f32x16& p0, f32x16& p1, const char* Ks, const char* KRs, const bf16x8* qr, const char* qrl, const f32x16& negm, int r32, int hi) {
; #pragma unroll
;   for (int d0 = 0; d0 < 8; ++d0) { int cb = (d0 * 16 + hi * 8) * 2;
;     bf16x8 b0 = *reinterpret_cast<const bf16x8*>(Ks + KSWZ(r32, cb));
;     bf16x8 b1 = *reinterpret_cast<const bf16x8*>(Ks + KSWZ(32 + r32, cb));
;     if (d0 == 0) { p0 = __builtin_amdgcn_mfma_f32_32x32x16_bf16(b0, qr[0], negm, 0, 0, 0); p1 = __builtin_amdgcn_mfma_f32_32x32x16_bf16(b1, qr[0], negm, 0, 0, 0); }
;     else { p0 = __builtin_amdgcn_mfma_f32_32x32x16_bf16(b0, qr[d0], p0, 0, 0, 0); p1 = __builtin_amdgcn_mfma_f32_32x32x16_bf16(b1, qr[d0], p1, 0, 0, 0); } }
; template <bool MLA> ...
;     ...
;   WAIT_BAR();
;   qkt<MLA>(pA0, pA1, K_lds, KR_lds, qr, qrl, negm, r32, hi); partialSM<true, false>(pA0, pA1, negm, m_reg, alA);
	ds_read_b128 v[2:5], v6 offset:49152
	ds_read_b128 v[6:9], v6 offset:57344
	s_waitcnt lgkmcnt(1)
	v_mfma_f32_32x32x16_bf16 v[50:65], v[2:5], v[158:161], v[18:33]
	v_or_b32_e32 v2, 32, v166
	v_bitop3_b32 v198, v2, v13, v70 bitop3:0xde
	v_lshlrev_b32_e32 v74, 1, v74
	v_and_b32_e32 v74, 32, v74
	s_movk_i32 s6, 0xc0
	v_and_or_b32 v0, v0, s6, v74
	s_cmp_lg_u32 0, -1
	s_waitcnt lgkmcnt(0)
	v_mfma_f32_32x32x16_bf16 v[34:49], v[6:9], v[158:161], v[18:33]
	v_add_u32_e32 v6, 0, v198
	ds_read_b128 v[2:5], v6 offset:49152
	ds_read_b128 v[6:9], v6 offset:57344
	s_cselect_b32 s6, 0, 0
	s_mul_i32 s8, s8, 0xc000
	s_mov_b32 s17, 2
	s_mov_b32 s16, 1
	s_mov_b32 s23, 0
	s_waitcnt lgkmcnt(1)
	v_mfma_f32_32x32x16_bf16 v[50:65], v[2:5], v[154:157], v[50:65]
	v_or_b32_e32 v2, 64, v166
	v_bitop3_b32 v197, v2, v13, v70 bitop3:0xde
	s_mov_b32 s18, -1
	v_lshl_add_u32 v167, v178, 2, s10
	v_mov_b32_e32 v169, v1
	v_mov_b32_e32 v171, v1
	v_mov_b32_e32 v180, 0
	s_waitcnt lgkmcnt(0)
	v_mfma_f32_32x32x16_bf16 v[34:49], v[6:9], v[154:157], v[34:49]
	v_add_u32_e32 v6, 0, v197
	ds_read_b128 v[2:5], v6 offset:49152
	ds_read_b128 v[6:9], v6 offset:57344
	v_mov_b32_e32 v200, 1.0
	s_waitcnt lgkmcnt(1)
	v_mfma_f32_32x32x16_bf16 v[50:65], v[2:5], v[150:153], v[50:65]
	v_or_b32_e32 v2, 0x60, v166
	v_bitop3_b32 v196, v2, v13, v70 bitop3:0xde
	s_waitcnt lgkmcnt(0)
	v_mfma_f32_32x32x16_bf16 v[34:49], v[6:9], v[150:153], v[34:49]
	v_add_u32_e32 v6, 0, v196
	ds_read_b128 v[2:5], v6 offset:49152
	ds_read_b128 v[6:9], v6 offset:57344
	s_waitcnt lgkmcnt(1)
	v_mfma_f32_32x32x16_bf16 v[50:65], v[2:5], v[146:149], v[50:65]
	v_or_b32_e32 v2, 0x80, v166
	v_bitop3_b32 v195, v2, v13, v70 bitop3:0xde
	s_waitcnt lgkmcnt(0)
	v_mfma_f32_32x32x16_bf16 v[34:49], v[6:9], v[146:149], v[34:49]
	v_add_u32_e32 v6, 0, v195
	ds_read_b128 v[2:5], v6 offset:49152
	ds_read_b128 v[6:9], v6 offset:57344
	s_waitcnt lgkmcnt(1)
	v_mfma_f32_32x32x16_bf16 v[50:65], v[2:5], v[142:145], v[50:65]
	v_or_b32_e32 v2, 0xa0, v166
	v_bitop3_b32 v183, v2, v13, v70 bitop3:0xde
	s_waitcnt lgkmcnt(0)
	v_mfma_f32_32x32x16_bf16 v[34:49], v[6:9], v[142:145], v[34:49]
	v_add_u32_e32 v6, 0, v183
	ds_read_b128 v[2:5], v6 offset:49152
	ds_read_b128 v[6:9], v6 offset:57344
	s_waitcnt lgkmcnt(1)
	v_mfma_f32_32x32x16_bf16 v[50:65], v[2:5], v[138:141], v[50:65]
	v_or_b32_e32 v4, 0xc0, v166
	v_bitop3_b32 v193, v4, v13, v70 bitop3:0xde
	v_add_u32_e32 v4, 0, v193
	ds_read_b128 v[14:17], v4 offset:57344
	ds_read_b128 v[66:69], v4 offset:49152
	v_mov_b32_e32 v2, v1
	v_mov_b32_e32 v3, v1
	v_mov_b32_e32 v4, v1
	s_waitcnt lgkmcnt(2)
	v_mfma_f32_32x32x16_bf16 v[34:49], v[6:9], v[138:141], v[34:49]
	v_mov_b32_e32 v5, v1
	v_mov_b32_e32 v6, v1
	v_mov_b32_e32 v7, v1
	v_mov_b32_e32 v8, v1
	v_mov_b32_e32 v9, v1
	s_waitcnt lgkmcnt(0)
	v_mfma_f32_32x32x16_bf16 v[50:65], v[66:69], v[134:137], v[50:65]
	v_or_b32_e32 v66, 0xe0, v166
	v_bitop3_b32 v194, v66, v13, v70 bitop3:0xde
	v_add_u32_e32 v13, 0, v194
	ds_read_b128 v[66:69], v13 offset:57344
	ds_read_b128 v[70:73], v13 offset:49152
	v_mov_b32_e32 v13, v1
	v_mfma_f32_32x32x16_bf16 v[34:49], v[14:17], v[134:137], v[34:49]
	v_mov_b32_e32 v16, v1
	v_mov_b32_e32 v17, v1
	v_mov_b32_e32 v14, v1
	v_mov_b32_e32 v15, v1
	s_waitcnt lgkmcnt(0)
; __device__ __forceinline__ float max3f(float a, float b, float c) { return __builtin_fmaxf(__builtin_fmaxf(a, b), c); }
; template <bool FIRST, bool MLA>
; __device__ __forceinline__ void partialSM(f32x16& p0, f32x16& p1, f32x16& negm, float& m_reg, float& alpha) {
;   float a = max3f(p0[0], p0[1], p1[0]), b = max3f(p0[2], p0[3], p1[1]); a = max3f(a, p1[2], p1[3]);
; #pragma unroll
;   for (int r = 4; r < 16; r += 4) { a = max3f(a, p0[r], p0[r + 1]); b = max3f(b, p0[r + 2], p0[r + 3]); a = max3f(a, p1[r], p1[r + 1]); b = max3f(b, p1[r + 2], p1[r + 3]); }
;   float pmax = fmaxf(a, b);
;   { auto rr = __builtin_amdgcn_permlane32_swap(__float_as_uint(pmax), __float_as_uint(pmax), false, false);
;     pmax = fmaxf(__uint_as_float(rr[0]), __uint_as_float(rr[1])); }
;   alpha = 1.f;
;   if constexpr (MLA) {
;     if (FIRST) m_reg = pmax;
;     else if (!__builtin_expect(__all(pmax - m_reg <= THR2), 1)) { const float mn = fmaxf(m_reg, pmax); alpha = __builtin_amdgcn_exp2f(m_reg - mn); m_reg = mn; }
; #pragma unroll
;     for (int r = 0; r < 16; ++r) { p0[r] -= m_reg; p1[r] -= m_reg; }
;   } else
;   if (FIRST || __builtin_expect(__any(pmax > THR2), 0)) {
;     const float d = FIRST ? pmax : fmaxf(pmax, 0.f);
; #pragma unroll
;     for (int r = 0; r < 16; ++r) { p0[r] -= d; p1[r] -= d; }
; #pragma unroll
;     for (int r = 0; r < 16; ++r) negm[r] -= d;
;     asm volatile("" : "+v"(negm));
;     if (!FIRST) alpha = __builtin_amdgcn_exp2f(-d);
;   }
; #pragma unroll
;   for (int r = 0; r < 16; ++r) p0[r] = __builtin_amdgcn_exp2f(p0[r]);
	v_mfma_f32_32x32x16_bf16 v[50:65], v[70:73], v[130:133], v[50:65]
	v_and_b32_e32 v70, 0x100, v75
	v_or3_b32 v181, v0, v70, v103
	v_add_u32_e32 v182, s6, v181
	v_cmp_gt_u32_e64 s[6:7], 32, v98
	v_mfma_f32_32x32x16_bf16 v[34:49], v[66:69], v[130:133], v[34:49]
	s_nop 6
	v_max_f32_e32 v0, v51, v51
	v_max_f32_e32 v66, v50, v50
	v_max_f32_e32 v0, v66, v0
	s_nop 1
	v_max3_f32 v66, v52, v53, v35
	v_max3_f32 v0, v0, v34, v36
	v_max3_f32 v0, v0, v37, v54
	v_max3_f32 v66, v66, v56, v57
	v_max3_f32 v0, v0, v55, v38
	v_max3_f32 v66, v66, v40, v41
	v_max3_f32 v0, v0, v39, v58
	v_max3_f32 v66, v66, v60, v61
	v_max3_f32 v0, v0, v59, v42
	v_max3_f32 v66, v66, v44, v45
	v_max3_f32 v0, v0, v43, v62
	v_max3_f32 v66, v66, v64, v65
	v_max3_f32 v0, v0, v63, v46
	v_max3_f32 v66, v66, v48, v49
	v_max3_f32 v0, v0, v47, v66
	v_mov_b32_e32 v66, v0
	s_nop 1
	v_permlane32_swap_b32_e32 v0, v66
	v_max_f32_e32 v66, v66, v66
	v_max_f32_e32 v0, v0, v0
	v_max_f32_e32 v0, v0, v66
	v_sub_f32_e32 v50, v50, v0
	v_sub_f32_e32 v51, v51, v0
	v_sub_f32_e32 v52, v52, v0
	v_sub_f32_e32 v53, v53, v0
	v_sub_f32_e32 v54, v54, v0
	v_sub_f32_e32 v55, v55, v0
	v_sub_f32_e32 v56, v56, v0
	v_sub_f32_e32 v57, v57, v0
	v_sub_f32_e32 v58, v58, v0
	v_sub_f32_e32 v59, v59, v0
	v_sub_f32_e32 v60, v60, v0
	v_sub_f32_e32 v61, v61, v0
	v_sub_f32_e32 v62, v62, v0
	v_sub_f32_e32 v63, v63, v0
	v_sub_f32_e32 v64, v64, v0
	v_sub_f32_e32 v65, v65, v0
	v_sub_f32_e32 v97, v49, v0
	v_sub_f32_e32 v96, v48, v0
	v_sub_f32_e32 v95, v47, v0
	v_sub_f32_e32 v94, v46, v0
	v_sub_f32_e32 v93, v45, v0
	v_sub_f32_e32 v92, v44, v0
	v_sub_f32_e32 v91, v43, v0
	v_sub_f32_e32 v90, v42, v0
	v_sub_f32_e32 v89, v41, v0
	v_sub_f32_e32 v88, v40, v0
	v_sub_f32_e32 v87, v39, v0
	v_sub_f32_e32 v86, v38, v0
	v_sub_f32_e32 v85, v37, v0
	v_sub_f32_e32 v84, v36, v0
	v_sub_f32_e32 v83, v35, v0
	v_sub_f32_e32 v82, v34, v0
	v_sub_f32_e32 v81, v33, v0
	v_sub_f32_e32 v80, v32, v0
	v_sub_f32_e32 v79, v31, v0
	v_sub_f32_e32 v78, v30, v0
	v_sub_f32_e32 v77, v29, v0
	v_sub_f32_e32 v76, v28, v0
	v_sub_f32_e32 v75, v27, v0
	v_sub_f32_e32 v74, v26, v0
	v_sub_f32_e32 v73, v25, v0
	v_sub_f32_e32 v72, v24, v0
	v_sub_f32_e32 v71, v23, v0
	v_sub_f32_e32 v70, v22, v0
	v_sub_f32_e32 v69, v21, v0
	v_sub_f32_e32 v68, v20, v0
	v_sub_f32_e32 v67, v19, v0
	v_sub_f32_e32 v66, v18, v0
	v_or_b32_e32 v0, s9, v101
	s_and_b32 s9, s13, 4
	s_lshl_b32 s9, s9, 6
	s_or_b32 s2, s2, s9
	s_add_u32 s2, s98, s2
	v_mov_b32_e32 v18, s8
	s_addc_u32 s3, s99, s3
	v_mad_u32_u24 v18, v99, s33, v18
	s_addk_i32 s8, 0x6000
	v_exp_f32_e32 v217, v50
	v_exp_f32_e32 v219, v51
	v_exp_f32_e32 v215, v52
	v_exp_f32_e32 v218, v53
	v_exp_f32_e32 v214, v54
	v_exp_f32_e32 v216, v55
	v_exp_f32_e32 v212, v56
	v_exp_f32_e32 v213, v57
	v_exp_f32_e32 v209, v58
	v_exp_f32_e32 v211, v59
	v_exp_f32_e32 v208, v60
	v_exp_f32_e32 v210, v61
	v_exp_f32_e32 v205, v62
	v_exp_f32_e32 v207, v63
	v_exp_f32_e32 v204, v64
	v_exp_f32_e32 v206, v65
	v_or3_b32 v0, v0, s19, v100
	v_or_b32_e32 v168, v18, v104
	v_mov_b32_e32 v18, s8
	v_mul_lo_u32 v0, v0, s26
	v_mad_u32_u24 v18, v99, s33, v18
	v_or3_b32 v0, v0, v102, v103
	v_or_b32_e32 v170, v18, v105
	v_mov_b64_e32 v[64:65], v[16:17]
	v_mov_b64_e32 v[48:49], v[16:17]
	v_mov_b64_e32 v[32:33], v[16:17]
	v_lshlrev_b32_e32 v0, 1, v0
	v_mov_b64_e32 v[62:63], v[14:15]
	v_mov_b64_e32 v[60:61], v[12:13]
	v_mov_b64_e32 v[58:59], v[10:11]
	v_mov_b64_e32 v[56:57], v[8:9]
	v_mov_b64_e32 v[54:55], v[6:7]
	v_mov_b64_e32 v[52:53], v[4:5]
	v_mov_b64_e32 v[50:51], v[2:3]
	v_mov_b64_e32 v[46:47], v[14:15]
	v_mov_b64_e32 v[44:45], v[12:13]
	v_mov_b64_e32 v[42:43], v[10:11]
	v_mov_b64_e32 v[40:41], v[8:9]
	v_mov_b64_e32 v[38:39], v[6:7]
	v_mov_b64_e32 v[36:37], v[4:5]
	v_mov_b64_e32 v[34:35], v[2:3]
	v_mov_b64_e32 v[30:31], v[14:15]
	v_mov_b64_e32 v[28:29], v[12:13]
	v_mov_b64_e32 v[26:27], v[10:11]
	v_mov_b64_e32 v[24:25], v[8:9]
	v_mov_b64_e32 v[22:23], v[6:7]
	v_mov_b64_e32 v[20:21], v[4:5]
	v_mov_b64_e32 v[18:19], v[2:3]
